# v20 + SiLU gate division via v_rcp_f32*numerator (f32) in attention/GLA epilogues with dead chain removed + causal epilogue gate rows prefetched up front
# speedup vs baseline: 1.0067x; 1.0067x over previous
.LBB0_417:
	v_pk_add_f32 v[64:65], v[80:81], 0 op_sel_hi:[1,0]
	s_lshl_b64 s[8:9], s[22:23], 12
	v_pk_add_f32 v[64:65], v[82:83], v[64:65]
	s_add_u32 s8, s42, s8
	v_pk_add_f32 v[64:65], v[84:85], v[64:65]
	s_addc_u32 s9, s43, s9
	v_pk_add_f32 v[64:65], v[86:87], v[64:65]
	s_add_u32 s8, s8, s91
	v_pk_add_f32 v[64:65], v[88:89], v[64:65]
	s_addc_u32 s9, s9, 0
	v_pk_add_f32 v[64:65], v[90:91], v[64:65]
	v_mov_b32_e32 v189, v181
	v_pk_add_f32 v[64:65], v[92:93], v[64:65]
	v_or_b32_e32 v180, s82, v197
	v_pk_add_f32 v[64:65], v[94:95], v[64:65]
	s_nop 0
	v_pk_add_f32 v[64:65], v[96:97], v[64:65]
	s_barrier
	v_pk_add_f32 v[64:65], v[98:99], v[64:65]
	s_nop 0
	v_pk_add_f32 v[64:65], v[100:101], v[64:65]
	s_nop 0
	v_pk_add_f32 v[64:65], v[102:103], v[64:65]
	s_nop 0
	v_pk_add_f32 v[64:65], v[104:105], v[64:65]
	s_nop 0
	v_pk_add_f32 v[64:65], v[106:107], v[64:65]
	s_nop 0
	v_pk_add_f32 v[64:65], v[108:109], v[64:65]
	s_nop 0
	v_pk_add_f32 v[64:65], v[110:111], v[64:65]
	s_nop 0
	v_add_f32_e32 v64, v64, v65
	v_add_f32_e32 v64, v154, v64
	ds_bpermute_b32 v65, v171, v64
	s_waitcnt lgkmcnt(0)
	v_add_f32_e32 v70, v64, v65
	v_div_scale_f32 v64, s[10:11], v70, v70, 1.0
	v_rcp_f32_e32 v71, v64
	s_add_u32 s10, s89, s91
	s_addc_u32 s11, s90, 0
	s_add_i32 s88, s88, s46
	v_fma_f32 v65, -v64, v71, 1.0
	v_fmac_f32_e32 v71, v65, v71
	v_div_scale_f32 v65, vcc, 1.0, v70, 1.0
	v_mul_f32_e32 v72, v65, v71
	v_fma_f32 v66, -v64, v72, v65
	v_fmac_f32_e32 v72, v66, v71
	v_fma_f32 v73, -v64, v72, v65
	v_lshl_add_u64 v[64:65], s[10:11], 0, v[188:189]
	s_mov_b64 s[10:11], 0x1c00
	v_lshl_add_u64 v[68:69], v[64:65], 0, s[10:11]
	v_mad_u64_u32 v[64:65], s[10:11], v180, s73, v[68:69]
	global_load_dwordx4 v[64:67], v[64:65], off
	v_div_fmas_f32 v71, v73, v71, v72
	v_div_fixup_f32 v70, v71, v70, 1.0
	v_pk_mul_f32 v[16:17], v[16:17], v[70:71] op_sel_hi:[1,0]
	v_pk_mul_f32 v[18:19], v[18:19], v[70:71] op_sel_hi:[1,0]
	v_pk_mul_f32 v[0:1], v[0:1], v[70:71] op_sel_hi:[1,0]
	v_pk_mul_f32 v[2:3], v[2:3], v[70:71] op_sel_hi:[1,0]
	v_cvt_pk_bf16_f32 v16, v16, v17
	v_cvt_pk_bf16_f32 v17, v18, v19
	v_pk_mul_f32 v[18:19], v[20:21], v[70:71] op_sel_hi:[1,0]
	v_pk_mul_f32 v[20:21], v[22:23], v[70:71] op_sel_hi:[1,0]
	v_cvt_pk_bf16_f32 v0, v0, v1
	v_cvt_pk_bf16_f32 v1, v2, v3
	v_pk_mul_f32 v[2:3], v[4:5], v[70:71] op_sel_hi:[1,0]
	v_pk_mul_f32 v[4:5], v[6:7], v[70:71] op_sel_hi:[1,0]
	v_mad_u64_u32 v[72:73], s[10:11], v170, s65, v[182:183]
	v_cvt_pk_bf16_f32 v18, v18, v19
	v_cvt_pk_bf16_f32 v19, v20, v21
	v_cvt_pk_bf16_f32 v2, v2, v3
	v_cvt_pk_bf16_f32 v3, v4, v5
	ds_write2_b64 v72, v[16:17], v[18:19] offset0:16 offset1:18
	v_pk_mul_f32 v[16:17], v[24:25], v[70:71] op_sel_hi:[1,0]
	v_pk_mul_f32 v[18:19], v[26:27], v[70:71] op_sel_hi:[1,0]
	ds_write2_b64 v72, v[0:1], v[2:3] offset0:24 offset1:26
	v_pk_mul_f32 v[0:1], v[8:9], v[70:71] op_sel_hi:[1,0]
	v_pk_mul_f32 v[2:3], v[10:11], v[70:71] op_sel_hi:[1,0]
	v_cvt_pk_bf16_f32 v16, v16, v17
	v_cvt_pk_bf16_f32 v17, v18, v19
	v_pk_mul_f32 v[18:19], v[28:29], v[70:71] op_sel_hi:[1,0]
	v_pk_mul_f32 v[20:21], v[30:31], v[70:71] op_sel_hi:[1,0]
	v_cvt_pk_bf16_f32 v0, v0, v1
	v_cvt_pk_bf16_f32 v1, v2, v3
	v_pk_mul_f32 v[2:3], v[12:13], v[70:71] op_sel_hi:[1,0]
	v_pk_mul_f32 v[4:5], v[14:15], v[70:71] op_sel_hi:[1,0]
	v_cvt_pk_bf16_f32 v18, v18, v19
	v_cvt_pk_bf16_f32 v19, v20, v21
	v_cvt_pk_bf16_f32 v2, v2, v3
	v_cvt_pk_bf16_f32 v3, v4, v5
	v_pk_mul_f32 v[48:49], v[48:49], v[70:71] op_sel_hi:[1,0]
	v_pk_mul_f32 v[50:51], v[50:51], v[70:71] op_sel_hi:[1,0]
	v_pk_mul_f32 v[32:33], v[32:33], v[70:71] op_sel_hi:[1,0]
	v_pk_mul_f32 v[34:35], v[34:35], v[70:71] op_sel_hi:[1,0]
	ds_write2_b64 v72, v[16:17], v[18:19] offset0:20 offset1:22
	ds_write2_b64 v72, v[0:1], v[2:3] offset0:28 offset1:30
	v_lshl_add_u64 v[0:1], s[8:9], 0, v[188:189]
	s_mov_b64 s[8:9], 0x5004c00
	v_cvt_pk_bf16_f32 v48, v48, v49
	v_cvt_pk_bf16_f32 v49, v50, v51
	v_pk_mul_f32 v[50:51], v[52:53], v[70:71] op_sel_hi:[1,0]
	v_pk_mul_f32 v[52:53], v[54:55], v[70:71] op_sel_hi:[1,0]
	v_cvt_pk_bf16_f32 v32, v32, v33
	v_cvt_pk_bf16_f32 v33, v34, v35
	v_pk_mul_f32 v[34:35], v[36:37], v[70:71] op_sel_hi:[1,0]
	v_pk_mul_f32 v[36:37], v[38:39], v[70:71] op_sel_hi:[1,0]
	v_lshl_add_u64 v[12:13], v[0:1], 0, s[8:9]
	v_cvt_pk_bf16_f32 v50, v50, v51
	v_cvt_pk_bf16_f32 v51, v52, v53
	v_cvt_pk_bf16_f32 v34, v34, v35
	v_cvt_pk_bf16_f32 v35, v36, v37
	ds_write2_b64 v72, v[48:49], v[50:51] offset1:2
	v_pk_mul_f32 v[48:49], v[56:57], v[70:71] op_sel_hi:[1,0]
	v_pk_mul_f32 v[50:51], v[58:59], v[70:71] op_sel_hi:[1,0]
	ds_write2_b64 v72, v[32:33], v[34:35] offset0:8 offset1:10
	v_pk_mul_f32 v[32:33], v[40:41], v[70:71] op_sel_hi:[1,0]
	v_pk_mul_f32 v[34:35], v[42:43], v[70:71] op_sel_hi:[1,0]
	v_cvt_pk_bf16_f32 v48, v48, v49
	v_cvt_pk_bf16_f32 v49, v50, v51
	v_pk_mul_f32 v[50:51], v[60:61], v[70:71] op_sel_hi:[1,0]
	v_pk_mul_f32 v[52:53], v[62:63], v[70:71] op_sel_hi:[1,0]
	v_cvt_pk_bf16_f32 v32, v32, v33
	v_cvt_pk_bf16_f32 v33, v34, v35
	v_pk_mul_f32 v[34:35], v[44:45], v[70:71] op_sel_hi:[1,0]
	v_pk_mul_f32 v[36:37], v[46:47], v[70:71] op_sel_hi:[1,0]
	v_cvt_pk_bf16_f32 v50, v50, v51
	v_cvt_pk_bf16_f32 v51, v52, v53
	v_cvt_pk_bf16_f32 v34, v34, v35
	v_cvt_pk_bf16_f32 v35, v36, v37
	ds_write2_b64 v72, v[48:49], v[50:51] offset0:4 offset1:6
	ds_write2_b64 v72, v[32:33], v[34:35] offset0:12 offset1:14
	s_waitcnt vmcnt(0)
	v_lshlrev_b32_e32 v18, 16, v64
	v_and_b32_e32 v16, 0xffff0000, v64
	v_mul_f32_e32 v0, 0xbfb8aa3b, v18
	v_mul_f32_e32 v1, 0xbfb8aa3b, v16
	v_exp_f32_e32 v0, v0
	v_exp_f32_e32 v1, v1
	v_mad_u64_u32 v[14:15], s[8:9], v180, s65, v[184:185]
	ds_read_b128 v[4:7], v14
	v_pk_add_f32 v[8:9], v[0:1], 1.0 op_sel_hi:[1,0]
	ds_read_b128 v[0:3], v14 offset:1088
	s_waitcnt lgkmcnt(1)
	v_lshlrev_b32_e32 v10, 16, v4
	v_and_b32_e32 v11, 0xffff0000, v4
	v_and_b32_e32 v21, 0xffff0000, v65
	v_rcp_f32_e32 v4, v9
	s_nop 0
	v_mul_f32_e32 v9, v16, v4
	v_mul_f32_e32 v17, 0xbfb8aa3b, v21
	v_lshlrev_b32_e32 v15, 16, v65
	v_mul_f32_e32 v16, 0xbfb8aa3b, v15
	v_exp_f32_e32 v16, v16
	v_exp_f32_e32 v17, v17
	v_rcp_f32_e32 v4, v8
	s_nop 0
	v_mul_f32_e32 v8, v18, v4
	v_pk_mul_f32 v[8:9], v[8:9], v[10:11]
	v_pk_add_f32 v[10:11], v[16:17], 1.0 op_sel_hi:[1,0]
	v_cvt_pk_bf16_f32 v4, v8, v9
	v_lshlrev_b32_e32 v8, 16, v5
	v_and_b32_e32 v9, 0xffff0000, v5
	v_lshlrev_b32_e32 v20, 16, v66
	v_rcp_f32_e32 v5, v11
	s_nop 0
	v_mul_f32_e32 v11, v21, v5
	v_and_b32_e32 v21, 0xffff0000, v66
	v_mul_f32_e32 v16, 0xbfb8aa3b, v20
	v_mul_f32_e32 v17, 0xbfb8aa3b, v21
	v_exp_f32_e32 v16, v16
	v_exp_f32_e32 v17, v17
	v_rcp_f32_e32 v5, v10
	s_nop 0
	v_mul_f32_e32 v10, v15, v5
	v_pk_mul_f32 v[8:9], v[10:11], v[8:9]
	v_pk_add_f32 v[10:11], v[16:17], 1.0 op_sel_hi:[1,0]
	v_cvt_pk_bf16_f32 v5, v8, v9
	v_lshlrev_b32_e32 v8, 16, v6
	v_and_b32_e32 v9, 0xffff0000, v6
	s_cmpk_lt_i32 s88, 0x100
	v_rcp_f32_e32 v6, v11
	s_nop 0
	v_mul_f32_e32 v11, v21, v6
	v_and_b32_e32 v21, 0xffff0000, v67
	v_lshlrev_b32_e32 v15, 16, v67
	v_mul_f32_e32 v16, 0xbfb8aa3b, v15
	v_mul_f32_e32 v17, 0xbfb8aa3b, v21
	v_exp_f32_e32 v16, v16
	v_exp_f32_e32 v17, v17
	v_rcp_f32_e32 v6, v10
	s_nop 0
	v_mul_f32_e32 v10, v20, v6
	v_pk_mul_f32 v[8:9], v[10:11], v[8:9]
	v_pk_add_f32 v[10:11], v[16:17], 1.0 op_sel_hi:[1,0]
	v_cvt_pk_bf16_f32 v6, v8, v9
	v_lshlrev_b32_e32 v8, 16, v7
	v_and_b32_e32 v9, 0xffff0000, v7
	v_rcp_f32_e32 v7, v11
	s_nop 0
	v_mul_f32_e32 v11, v21, v7
	v_rcp_f32_e32 v7, v10
	s_nop 0
	v_mul_f32_e32 v10, v15, v7
	v_pk_mul_f32 v[8:9], v[10:11], v[8:9]
	s_waitcnt lgkmcnt(0)
	v_lshlrev_b32_e32 v16, 16, v0
	v_cvt_pk_bf16_f32 v7, v8, v9
	v_lshlrev_b64 v[8:9], 12, v[180:181]
	v_lshl_add_u64 v[8:9], v[12:13], 0, v[8:9]
	global_store_dwordx4 v[8:9], v[4:7], off sc1
	v_or_b32_e32 v8, 4, v180
	v_and_b32_e32 v17, 0xffff0000, v0
	v_mad_u64_u32 v[4:5], s[8:9], v8, s73, v[68:69]
	global_load_dwordx4 v[4:7], v[4:5], off
	s_waitcnt vmcnt(0)
	v_lshlrev_b32_e32 v15, 16, v4
	v_and_b32_e32 v4, 0xffff0000, v4
	v_mul_f32_e32 v9, 0xbfb8aa3b, v15
	v_exp_f32_e32 v10, v9
	v_mul_f32_e32 v9, 0xbfb8aa3b, v4
	v_exp_f32_e32 v11, v9
	v_mov_b32_e32 v9, v181
	v_pk_add_f32 v[10:11], v[10:11], 1.0 op_sel_hi:[1,0]
	s_nop 0
	s_nop 0
	v_rcp_f32_e32 v0, v11
	s_nop 0
	v_mul_f32_e32 v11, v4, v0
	v_and_b32_e32 v20, 0xffff0000, v5
	v_lshlrev_b32_e32 v18, 16, v5
	v_mul_f32_e32 v4, 0xbfb8aa3b, v18
	v_mul_f32_e32 v5, 0xbfb8aa3b, v20
	v_exp_f32_e32 v4, v4
	v_exp_f32_e32 v5, v5
	v_rcp_f32_e32 v0, v10
	s_nop 0
	v_mul_f32_e32 v10, v15, v0
	v_pk_mul_f32 v[10:11], v[10:11], v[16:17]
	v_pk_add_f32 v[4:5], v[4:5], 1.0 op_sel_hi:[1,0]
	v_cvt_pk_bf16_f32 v0, v10, v11
	v_lshlrev_b32_e32 v10, 16, v1
	v_and_b32_e32 v11, 0xffff0000, v1
	v_rcp_f32_e32 v1, v5
	s_nop 0
	v_mul_f32_e32 v5, v20, v1
	v_lshlrev_b32_e32 v15, 16, v6
	v_and_b32_e32 v6, 0xffff0000, v6
	v_mul_f32_e32 v16, 0xbfb8aa3b, v15
	v_mul_f32_e32 v17, 0xbfb8aa3b, v6
	v_exp_f32_e32 v16, v16
	v_exp_f32_e32 v17, v17
	v_rcp_f32_e32 v1, v4
	s_nop 0
	v_mul_f32_e32 v4, v18, v1
	v_pk_mul_f32 v[4:5], v[4:5], v[10:11]
	v_pk_add_f32 v[10:11], v[16:17], 1.0 op_sel_hi:[1,0]
	v_cvt_pk_bf16_f32 v1, v4, v5
	v_lshlrev_b32_e32 v4, 16, v2
	v_and_b32_e32 v5, 0xffff0000, v2
	v_rcp_f32_e32 v2, v11
	s_nop 0
	v_mul_f32_e32 v11, v6, v2
	v_and_b32_e32 v18, 0xffff0000, v7
	v_lshlrev_b32_e32 v16, 16, v7
	v_mul_f32_e32 v6, 0xbfb8aa3b, v16
	v_mul_f32_e32 v7, 0xbfb8aa3b, v18
	v_exp_f32_e32 v6, v6
	v_exp_f32_e32 v7, v7
	v_rcp_f32_e32 v2, v10
	s_nop 0
	v_mul_f32_e32 v10, v15, v2
	v_pk_mul_f32 v[4:5], v[10:11], v[4:5]
	v_pk_add_f32 v[6:7], v[6:7], 1.0 op_sel_hi:[1,0]
	v_cvt_pk_bf16_f32 v2, v4, v5
	v_lshlrev_b32_e32 v4, 16, v3
	v_and_b32_e32 v5, 0xffff0000, v3
	v_rcp_f32_e32 v3, v7
	s_nop 0
	v_mul_f32_e32 v7, v18, v3
	v_rcp_f32_e32 v3, v6
	s_nop 0
	v_mul_f32_e32 v6, v16, v3
	v_pk_mul_f32 v[4:5], v[6:7], v[4:5]
	v_or_b32_e32 v16, 8, v180
	v_cvt_pk_bf16_f32 v3, v4, v5
	v_lshlrev_b64 v[4:5], 12, v[8:9]
	v_lshl_add_u64 v[4:5], v[12:13], 0, v[4:5]
	global_store_dwordx4 v[4:5], v[0:3], off sc1
	ds_read_b128 v[4:7], v14 offset:2176
	v_mov_b32_e32 v17, v181
	v_mad_u64_u32 v[0:1], s[8:9], v16, s73, v[68:69]
	global_load_dwordx4 v[8:11], v[0:1], off
	s_waitcnt vmcnt(0)
	v_lshlrev_b32_e32 v15, 16, v8
	v_and_b32_e32 v8, 0xffff0000, v8
	v_mul_f32_e32 v0, 0xbfb8aa3b, v15
	v_mul_f32_e32 v1, 0xbfb8aa3b, v8
	v_exp_f32_e32 v0, v0
	v_exp_f32_e32 v1, v1
	s_nop 0
	v_pk_add_f32 v[18:19], v[0:1], 1.0 op_sel_hi:[1,0]
	s_nop 0
	ds_read_b128 v[0:3], v14 offset:3264
	s_waitcnt lgkmcnt(1)
	v_lshlrev_b32_e32 v20, 16, v4
	v_and_b32_e32 v21, 0xffff0000, v4
	v_rcp_f32_e32 v4, v19
	s_nop 0
	v_mul_f32_e32 v19, v8, v4
	v_and_b32_e32 v24, 0xffff0000, v9
	v_lshlrev_b32_e32 v22, 16, v9
	v_mul_f32_e32 v8, 0xbfb8aa3b, v22
	v_mul_f32_e32 v9, 0xbfb8aa3b, v24
	v_exp_f32_e32 v8, v8
	v_exp_f32_e32 v9, v9
	v_rcp_f32_e32 v4, v18
	s_nop 0
	v_mul_f32_e32 v18, v15, v4
	v_pk_mul_f32 v[18:19], v[18:19], v[20:21]
	v_pk_add_f32 v[8:9], v[8:9], 1.0 op_sel_hi:[1,0]
	v_cvt_pk_bf16_f32 v4, v18, v19
	v_lshlrev_b32_e32 v18, 16, v5
	v_and_b32_e32 v19, 0xffff0000, v5
	v_rcp_f32_e32 v5, v9
	s_nop 0
	v_mul_f32_e32 v9, v24, v5
	v_lshlrev_b32_e32 v15, 16, v10
	v_and_b32_e32 v10, 0xffff0000, v10
	v_mul_f32_e32 v20, 0xbfb8aa3b, v15
	v_mul_f32_e32 v21, 0xbfb8aa3b, v10
	v_exp_f32_e32 v20, v20
	v_exp_f32_e32 v21, v21
	v_rcp_f32_e32 v5, v8
	s_nop 0
	v_mul_f32_e32 v8, v22, v5
	v_pk_mul_f32 v[8:9], v[8:9], v[18:19]
	v_pk_add_f32 v[18:19], v[20:21], 1.0 op_sel_hi:[1,0]
	v_cvt_pk_bf16_f32 v5, v8, v9
	v_lshlrev_b32_e32 v8, 16, v6
	v_and_b32_e32 v9, 0xffff0000, v6
	v_rcp_f32_e32 v6, v19
	s_nop 0
	v_mul_f32_e32 v19, v10, v6
	v_and_b32_e32 v22, 0xffff0000, v11
	v_lshlrev_b32_e32 v20, 16, v11
	v_mul_f32_e32 v10, 0xbfb8aa3b, v20
	v_mul_f32_e32 v11, 0xbfb8aa3b, v22
	v_exp_f32_e32 v10, v10
	v_exp_f32_e32 v11, v11
	v_rcp_f32_e32 v6, v18
	s_nop 0
	v_mul_f32_e32 v18, v15, v6
	v_pk_mul_f32 v[8:9], v[18:19], v[8:9]
	v_pk_add_f32 v[10:11], v[10:11], 1.0 op_sel_hi:[1,0]
	v_cvt_pk_bf16_f32 v6, v8, v9
	v_lshlrev_b32_e32 v8, 16, v7
	v_and_b32_e32 v9, 0xffff0000, v7
	v_rcp_f32_e32 v7, v11
	s_nop 0
	v_mul_f32_e32 v11, v22, v7
	v_rcp_f32_e32 v7, v10
	s_nop 0
	v_mul_f32_e32 v10, v20, v7
	v_pk_mul_f32 v[8:9], v[10:11], v[8:9]
	s_nop 0
	v_cvt_pk_bf16_f32 v7, v8, v9
	v_lshlrev_b64 v[8:9], 12, v[16:17]
	v_lshl_add_u64 v[8:9], v[12:13], 0, v[8:9]
	global_store_dwordx4 v[8:9], v[4:7], off sc1
	v_or_b32_e32 v8, 12, v180
	s_waitcnt lgkmcnt(0)
	v_lshlrev_b32_e32 v16, 16, v0
	v_mad_u64_u32 v[4:5], s[8:9], v8, s73, v[68:69]
	global_load_dwordx4 v[4:7], v[4:5], off
	v_and_b32_e32 v17, 0xffff0000, v0
	s_waitcnt vmcnt(0)
	v_lshlrev_b32_e32 v15, 16, v4
	v_and_b32_e32 v4, 0xffff0000, v4
	v_mul_f32_e32 v9, 0xbfb8aa3b, v15
	v_exp_f32_e32 v10, v9
	v_mul_f32_e32 v9, 0xbfb8aa3b, v4
	v_exp_f32_e32 v11, v9
	v_mov_b32_e32 v9, v181
	v_pk_add_f32 v[10:11], v[10:11], 1.0 op_sel_hi:[1,0]
	s_nop 0
	s_nop 0
	v_rcp_f32_e32 v0, v11
	s_nop 0
	v_mul_f32_e32 v11, v4, v0
	v_and_b32_e32 v20, 0xffff0000, v5
	v_lshlrev_b32_e32 v18, 16, v5
	v_mul_f32_e32 v4, 0xbfb8aa3b, v18
	v_mul_f32_e32 v5, 0xbfb8aa3b, v20
	v_exp_f32_e32 v4, v4
	v_exp_f32_e32 v5, v5
	v_rcp_f32_e32 v0, v10
	s_nop 0
	v_mul_f32_e32 v10, v15, v0
	v_pk_mul_f32 v[10:11], v[10:11], v[16:17]
	v_pk_add_f32 v[4:5], v[4:5], 1.0 op_sel_hi:[1,0]
	v_cvt_pk_bf16_f32 v0, v10, v11
	v_lshlrev_b32_e32 v10, 16, v1
	v_and_b32_e32 v11, 0xffff0000, v1
	v_rcp_f32_e32 v1, v5
	s_nop 0
	v_mul_f32_e32 v5, v20, v1
	v_lshlrev_b32_e32 v15, 16, v6
	v_and_b32_e32 v6, 0xffff0000, v6
	v_mul_f32_e32 v16, 0xbfb8aa3b, v15
	v_mul_f32_e32 v17, 0xbfb8aa3b, v6
	v_exp_f32_e32 v16, v16
	v_exp_f32_e32 v17, v17
	v_rcp_f32_e32 v1, v4
	s_nop 0
	v_mul_f32_e32 v4, v18, v1
	v_pk_mul_f32 v[4:5], v[4:5], v[10:11]
	v_pk_add_f32 v[10:11], v[16:17], 1.0 op_sel_hi:[1,0]
	v_cvt_pk_bf16_f32 v1, v4, v5
	v_lshlrev_b32_e32 v4, 16, v2
	v_and_b32_e32 v5, 0xffff0000, v2
	v_rcp_f32_e32 v2, v11
	s_nop 0
	v_mul_f32_e32 v11, v6, v2
	v_and_b32_e32 v18, 0xffff0000, v7
	v_lshlrev_b32_e32 v16, 16, v7
	v_mul_f32_e32 v6, 0xbfb8aa3b, v16
	v_mul_f32_e32 v7, 0xbfb8aa3b, v18
	v_exp_f32_e32 v6, v6
	v_exp_f32_e32 v7, v7
	v_rcp_f32_e32 v2, v10
	s_nop 0
	v_mul_f32_e32 v10, v15, v2
	v_pk_mul_f32 v[4:5], v[10:11], v[4:5]
	v_pk_add_f32 v[6:7], v[6:7], 1.0 op_sel_hi:[1,0]
	v_cvt_pk_bf16_f32 v2, v4, v5
	v_lshlrev_b32_e32 v4, 16, v3
	v_and_b32_e32 v5, 0xffff0000, v3
	v_rcp_f32_e32 v3, v7
	s_nop 0
	v_mul_f32_e32 v7, v18, v3
	v_rcp_f32_e32 v3, v6
	s_nop 0
	v_mul_f32_e32 v6, v16, v3
	v_pk_mul_f32 v[4:5], v[6:7], v[4:5]
	v_or_b32_e32 v16, 16, v180
	v_cvt_pk_bf16_f32 v3, v4, v5
	v_lshlrev_b64 v[4:5], 12, v[8:9]
	v_lshl_add_u64 v[4:5], v[12:13], 0, v[4:5]
	global_store_dwordx4 v[4:5], v[0:3], off sc1
	ds_read_b128 v[4:7], v14 offset:4352
	v_mov_b32_e32 v17, v181
	v_mad_u64_u32 v[0:1], s[8:9], v16, s73, v[68:69]
	global_load_dwordx4 v[8:11], v[0:1], off
	s_waitcnt vmcnt(0)
	v_lshlrev_b32_e32 v15, 16, v8
	v_and_b32_e32 v8, 0xffff0000, v8
	v_mul_f32_e32 v0, 0xbfb8aa3b, v15
	v_mul_f32_e32 v1, 0xbfb8aa3b, v8
	v_exp_f32_e32 v0, v0
	v_exp_f32_e32 v1, v1
	s_nop 0
	v_pk_add_f32 v[18:19], v[0:1], 1.0 op_sel_hi:[1,0]
	s_nop 0
	ds_read_b128 v[0:3], v14 offset:5440
	s_waitcnt lgkmcnt(1)
	v_lshlrev_b32_e32 v20, 16, v4
	v_and_b32_e32 v21, 0xffff0000, v4
	v_div_scale_f32 v22, s[8:9], v18, v18, v15
	v_rcp_f32_e32 v25, v22
	v_rcp_f32_e32 v4, v19
	s_nop 0
	v_mul_f32_e32 v19, v8, v4
	v_and_b32_e32 v24, 0xffff0000, v9
	v_fma_f32 v4, -v22, v25, 1.0
	v_fmac_f32_e32 v25, v4, v25
	v_lshlrev_b32_e32 v22, 16, v9
	v_mul_f32_e32 v8, 0xbfb8aa3b, v22
	v_mul_f32_e32 v9, 0xbfb8aa3b, v24
	v_exp_f32_e32 v8, v8
	v_exp_f32_e32 v9, v9
	v_rcp_f32_e32 v4, v18
	s_nop 0
	v_mul_f32_e32 v18, v15, v4
	v_pk_mul_f32 v[18:19], v[18:19], v[20:21]
	v_pk_add_f32 v[8:9], v[8:9], 1.0 op_sel_hi:[1,0]
	v_cvt_pk_bf16_f32 v4, v18, v19
	v_lshlrev_b32_e32 v18, 16, v5
	v_and_b32_e32 v19, 0xffff0000, v5
	v_rcp_f32_e32 v5, v9
	s_nop 0
	v_mul_f32_e32 v9, v24, v5
	v_lshlrev_b32_e32 v15, 16, v10
	v_and_b32_e32 v10, 0xffff0000, v10
	v_mul_f32_e32 v20, 0xbfb8aa3b, v15
	v_mul_f32_e32 v21, 0xbfb8aa3b, v10
	v_exp_f32_e32 v20, v20
	v_exp_f32_e32 v21, v21
	v_rcp_f32_e32 v5, v8
	s_nop 0
	v_mul_f32_e32 v8, v22, v5
	v_pk_mul_f32 v[8:9], v[8:9], v[18:19]
	v_pk_add_f32 v[18:19], v[20:21], 1.0 op_sel_hi:[1,0]
	v_cvt_pk_bf16_f32 v5, v8, v9
	v_lshlrev_b32_e32 v8, 16, v6
	v_and_b32_e32 v9, 0xffff0000, v6
	v_rcp_f32_e32 v6, v19
	s_nop 0
	v_mul_f32_e32 v19, v10, v6
	v_and_b32_e32 v22, 0xffff0000, v11
	v_lshlrev_b32_e32 v20, 16, v11
	v_mul_f32_e32 v10, 0xbfb8aa3b, v20
	v_mul_f32_e32 v11, 0xbfb8aa3b, v22
	v_exp_f32_e32 v10, v10
	v_exp_f32_e32 v11, v11
	v_rcp_f32_e32 v6, v18
	s_nop 0
	v_mul_f32_e32 v18, v15, v6
	v_pk_mul_f32 v[8:9], v[18:19], v[8:9]
	v_pk_add_f32 v[10:11], v[10:11], 1.0 op_sel_hi:[1,0]
	v_cvt_pk_bf16_f32 v6, v8, v9
	v_lshlrev_b32_e32 v8, 16, v7
	v_and_b32_e32 v9, 0xffff0000, v7
	v_rcp_f32_e32 v7, v11
	s_nop 0
	v_mul_f32_e32 v11, v22, v7
	v_rcp_f32_e32 v7, v10
	s_nop 0
	v_mul_f32_e32 v10, v20, v7
	v_pk_mul_f32 v[8:9], v[10:11], v[8:9]
	s_nop 0
	v_cvt_pk_bf16_f32 v7, v8, v9
	v_lshlrev_b64 v[8:9], 12, v[16:17]
	v_lshl_add_u64 v[8:9], v[12:13], 0, v[8:9]
	global_store_dwordx4 v[8:9], v[4:7], off sc1
	v_or_b32_e32 v8, 20, v180
	s_waitcnt lgkmcnt(0)
	v_lshlrev_b32_e32 v16, 16, v0
	v_mad_u64_u32 v[4:5], s[8:9], v8, s73, v[68:69]
	global_load_dwordx4 v[4:7], v[4:5], off
	v_and_b32_e32 v17, 0xffff0000, v0
	s_waitcnt vmcnt(0)
	v_lshlrev_b32_e32 v15, 16, v4
	v_and_b32_e32 v4, 0xffff0000, v4
	v_mul_f32_e32 v9, 0xbfb8aa3b, v15
	v_exp_f32_e32 v10, v9
	v_mul_f32_e32 v9, 0xbfb8aa3b, v4
	v_exp_f32_e32 v11, v9
	v_mov_b32_e32 v9, v181
	v_pk_add_f32 v[10:11], v[10:11], 1.0 op_sel_hi:[1,0]
	s_nop 0
	s_nop 0
	v_rcp_f32_e32 v0, v11
	s_nop 0
	v_mul_f32_e32 v11, v4, v0
	v_and_b32_e32 v20, 0xffff0000, v5
	v_lshlrev_b32_e32 v18, 16, v5
	v_mul_f32_e32 v4, 0xbfb8aa3b, v18
	v_mul_f32_e32 v5, 0xbfb8aa3b, v20
	v_exp_f32_e32 v4, v4
	v_exp_f32_e32 v5, v5
	v_rcp_f32_e32 v0, v10
	s_nop 0
	v_mul_f32_e32 v10, v15, v0
	v_pk_mul_f32 v[10:11], v[10:11], v[16:17]
	v_pk_add_f32 v[4:5], v[4:5], 1.0 op_sel_hi:[1,0]
	v_cvt_pk_bf16_f32 v0, v10, v11
	v_lshlrev_b32_e32 v10, 16, v1
	v_and_b32_e32 v11, 0xffff0000, v1
	v_rcp_f32_e32 v1, v5
	s_nop 0
	v_mul_f32_e32 v5, v20, v1
	v_lshlrev_b32_e32 v15, 16, v6
	v_and_b32_e32 v6, 0xffff0000, v6
	v_mul_f32_e32 v16, 0xbfb8aa3b, v15
	v_mul_f32_e32 v17, 0xbfb8aa3b, v6
	v_exp_f32_e32 v16, v16
	v_exp_f32_e32 v17, v17
	v_rcp_f32_e32 v1, v4
	s_nop 0
	v_mul_f32_e32 v4, v18, v1
	v_pk_mul_f32 v[4:5], v[4:5], v[10:11]
	v_pk_add_f32 v[10:11], v[16:17], 1.0 op_sel_hi:[1,0]
	v_cvt_pk_bf16_f32 v1, v4, v5
	v_lshlrev_b32_e32 v4, 16, v2
	v_and_b32_e32 v5, 0xffff0000, v2
	v_rcp_f32_e32 v2, v11
	s_nop 0
	v_mul_f32_e32 v11, v6, v2
	v_and_b32_e32 v18, 0xffff0000, v7
	v_lshlrev_b32_e32 v16, 16, v7
	v_mul_f32_e32 v6, 0xbfb8aa3b, v16
	v_mul_f32_e32 v7, 0xbfb8aa3b, v18
	v_exp_f32_e32 v6, v6
	v_exp_f32_e32 v7, v7
	v_rcp_f32_e32 v2, v10
	s_nop 0
	v_mul_f32_e32 v10, v15, v2
	v_pk_mul_f32 v[4:5], v[10:11], v[4:5]
	v_pk_add_f32 v[6:7], v[6:7], 1.0 op_sel_hi:[1,0]
	v_cvt_pk_bf16_f32 v2, v4, v5
	v_lshlrev_b32_e32 v4, 16, v3
	v_and_b32_e32 v5, 0xffff0000, v3
	v_rcp_f32_e32 v3, v7
	s_nop 0
	v_mul_f32_e32 v7, v18, v3
	v_rcp_f32_e32 v3, v6
	s_nop 0
	v_mul_f32_e32 v6, v16, v3
	v_pk_mul_f32 v[4:5], v[6:7], v[4:5]
	v_or_b32_e32 v16, 24, v180
	v_cvt_pk_bf16_f32 v3, v4, v5
	v_lshlrev_b64 v[4:5], 12, v[8:9]
	v_lshl_add_u64 v[4:5], v[12:13], 0, v[4:5]
	global_store_dwordx4 v[4:5], v[0:3], off sc1
	ds_read_b128 v[4:7], v14 offset:6528
	v_mov_b32_e32 v17, v181
	v_mad_u64_u32 v[0:1], s[8:9], v16, s73, v[68:69]
	global_load_dwordx4 v[8:11], v[0:1], off
	v_or_b32_e32 v180, 28, v180
	s_waitcnt vmcnt(0)
	v_lshlrev_b32_e32 v20, 16, v8
	v_and_b32_e32 v8, 0xffff0000, v8
	v_mul_f32_e32 v0, 0xbfb8aa3b, v20
	v_mul_f32_e32 v1, 0xbfb8aa3b, v8
	v_exp_f32_e32 v0, v0
	v_exp_f32_e32 v1, v1
	s_nop 0
	v_pk_add_f32 v[18:19], v[0:1], 1.0 op_sel_hi:[1,0]
	s_nop 0
	ds_read_b128 v[0:3], v14 offset:7616
	s_waitcnt lgkmcnt(1)
	v_lshlrev_b32_e32 v14, 16, v4
	v_and_b32_e32 v15, 0xffff0000, v4
	v_div_scale_f32 v21, s[8:9], v18, v18, v20
	v_rcp_f32_e32 v24, v21
	v_rcp_f32_e32 v4, v19
	s_nop 0
	v_mul_f32_e32 v19, v8, v4
	v_and_b32_e32 v23, 0xffff0000, v9
	v_fma_f32 v4, -v21, v24, 1.0
	v_fmac_f32_e32 v24, v4, v24
	v_lshlrev_b32_e32 v21, 16, v9
	v_mul_f32_e32 v8, 0xbfb8aa3b, v21
	v_mul_f32_e32 v9, 0xbfb8aa3b, v23
	v_exp_f32_e32 v8, v8
	v_exp_f32_e32 v9, v9
	v_rcp_f32_e32 v4, v18
	s_nop 0
	v_mul_f32_e32 v18, v20, v4
	v_pk_mul_f32 v[14:15], v[18:19], v[14:15]
	v_pk_add_f32 v[8:9], v[8:9], 1.0 op_sel_hi:[1,0]
	v_cvt_pk_bf16_f32 v4, v14, v15
	v_lshlrev_b32_e32 v14, 16, v5
	v_and_b32_e32 v15, 0xffff0000, v5
	v_div_scale_f32 v18, s[8:9], v8, v8, v21
	v_rcp_f32_e32 v22, v18
	v_rcp_f32_e32 v5, v9
	s_nop 0
	v_mul_f32_e32 v9, v23, v5
	v_lshlrev_b32_e32 v23, 16, v10
	v_fma_f32 v5, -v18, v22, 1.0
	v_fmac_f32_e32 v22, v5, v22
	v_and_b32_e32 v10, 0xffff0000, v10
	v_mul_f32_e32 v18, 0xbfb8aa3b, v23
	v_mul_f32_e32 v19, 0xbfb8aa3b, v10
	v_exp_f32_e32 v18, v18
	v_exp_f32_e32 v19, v19
	v_rcp_f32_e32 v5, v8
	s_nop 0
	v_mul_f32_e32 v8, v21, v5
	v_pk_mul_f32 v[8:9], v[8:9], v[14:15]
	v_pk_add_f32 v[14:15], v[18:19], 1.0 op_sel_hi:[1,0]
	v_cvt_pk_bf16_f32 v5, v8, v9
	v_lshlrev_b32_e32 v8, 16, v6
	v_and_b32_e32 v9, 0xffff0000, v6
	v_rcp_f32_e32 v6, v15
	s_nop 0
	v_mul_f32_e32 v15, v10, v6
	v_and_b32_e32 v20, 0xffff0000, v11
	v_lshlrev_b32_e32 v18, 16, v11
	v_mul_f32_e32 v10, 0xbfb8aa3b, v18
	v_mul_f32_e32 v11, 0xbfb8aa3b, v20
	v_exp_f32_e32 v10, v10
	v_exp_f32_e32 v11, v11
	v_rcp_f32_e32 v6, v14
	s_nop 0
	v_mul_f32_e32 v14, v23, v6
	v_pk_mul_f32 v[8:9], v[14:15], v[8:9]
	v_pk_add_f32 v[10:11], v[10:11], 1.0 op_sel_hi:[1,0]
	v_cvt_pk_bf16_f32 v6, v8, v9
	v_lshlrev_b32_e32 v8, 16, v7
	v_and_b32_e32 v9, 0xffff0000, v7
	v_div_scale_f32 v14, s[8:9], v10, v10, v18
	v_rcp_f32_e32 v21, v14
	v_rcp_f32_e32 v7, v11
	s_nop 0
	v_mul_f32_e32 v11, v20, v7
	v_fma_f32 v7, -v14, v21, 1.0
	v_fmac_f32_e32 v21, v7, v21
	v_div_scale_f32 v7, vcc, v18, v10, v18
	v_mul_f32_e32 v15, v7, v21
	v_fma_f32 v19, -v14, v15, v7
	v_rcp_f32_e32 v7, v10
	s_nop 0
	v_mul_f32_e32 v10, v18, v7
	v_pk_mul_f32 v[8:9], v[10:11], v[8:9]
	s_waitcnt lgkmcnt(0)
	v_lshlrev_b32_e32 v10, 16, v0
	v_cvt_pk_bf16_f32 v7, v8, v9
	v_lshlrev_b64 v[8:9], 12, v[16:17]
	v_lshl_add_u64 v[8:9], v[12:13], 0, v[8:9]
	global_store_dwordx4 v[8:9], v[4:7], off sc1
	v_and_b32_e32 v11, 0xffff0000, v0
	s_nop 0
	v_mad_u64_u32 v[4:5], s[8:9], v180, s73, v[68:69]
	global_load_dwordx4 v[4:7], v[4:5], off
	s_waitcnt vmcnt(0)
	v_lshlrev_b32_e32 v14, 16, v4
	v_and_b32_e32 v4, 0xffff0000, v4
	v_mul_f32_e32 v8, 0xbfb8aa3b, v14
	v_mul_f32_e32 v9, 0xbfb8aa3b, v4
	v_exp_f32_e32 v8, v8
	v_exp_f32_e32 v9, v9
	s_nop 0
	v_pk_add_f32 v[8:9], v[8:9], 1.0 op_sel_hi:[1,0]
	s_nop 0
	s_nop 0
	v_div_scale_f32 v15, s[8:9], v8, v8, v14
	v_rcp_f32_e32 v18, v15
	v_rcp_f32_e32 v0, v9
	s_nop 0
	v_mul_f32_e32 v9, v4, v0
	v_and_b32_e32 v17, 0xffff0000, v5
	v_fma_f32 v0, -v15, v18, 1.0
	v_fmac_f32_e32 v18, v0, v18
	v_lshlrev_b32_e32 v15, 16, v5
	v_mul_f32_e32 v4, 0xbfb8aa3b, v15
	v_mul_f32_e32 v5, 0xbfb8aa3b, v17
	v_exp_f32_e32 v4, v4
	v_exp_f32_e32 v5, v5
	v_rcp_f32_e32 v0, v8
	s_nop 0
	v_mul_f32_e32 v8, v14, v0
	v_pk_mul_f32 v[8:9], v[8:9], v[10:11]
	v_pk_add_f32 v[4:5], v[4:5], 1.0 op_sel_hi:[1,0]
	v_cvt_pk_bf16_f32 v0, v8, v9
	v_lshlrev_b32_e32 v8, 16, v1
	v_and_b32_e32 v9, 0xffff0000, v1
	v_div_scale_f32 v10, s[8:9], v4, v4, v15
	v_rcp_f32_e32 v16, v10
	v_rcp_f32_e32 v1, v5
	s_nop 0
	v_mul_f32_e32 v5, v17, v1
	v_lshlrev_b32_e32 v17, 16, v6
	v_fma_f32 v1, -v10, v16, 1.0
	v_fmac_f32_e32 v16, v1, v16
	v_and_b32_e32 v6, 0xffff0000, v6
	v_mul_f32_e32 v10, 0xbfb8aa3b, v17
	v_mul_f32_e32 v11, 0xbfb8aa3b, v6
	v_exp_f32_e32 v10, v10
	v_exp_f32_e32 v11, v11
	v_rcp_f32_e32 v1, v4
	s_nop 0
	v_mul_f32_e32 v4, v15, v1
	v_pk_mul_f32 v[4:5], v[4:5], v[8:9]
	v_pk_add_f32 v[8:9], v[10:11], 1.0 op_sel_hi:[1,0]
	v_cvt_pk_bf16_f32 v1, v4, v5
	v_lshlrev_b32_e32 v4, 16, v2
	v_and_b32_e32 v5, 0xffff0000, v2
	v_rcp_f32_e32 v2, v9
	s_nop 0
	v_mul_f32_e32 v9, v6, v2
	v_and_b32_e32 v14, 0xffff0000, v7
	v_lshlrev_b32_e32 v10, 16, v7
	v_mul_f32_e32 v6, 0xbfb8aa3b, v10
	v_mul_f32_e32 v7, 0xbfb8aa3b, v14
	v_exp_f32_e32 v6, v6
	v_exp_f32_e32 v7, v7
	v_rcp_f32_e32 v2, v8
	s_nop 0
	v_mul_f32_e32 v8, v17, v2
	v_pk_mul_f32 v[4:5], v[8:9], v[4:5]
	v_pk_add_f32 v[6:7], v[6:7], 1.0 op_sel_hi:[1,0]
	v_cvt_pk_bf16_f32 v2, v4, v5
	v_lshlrev_b32_e32 v4, 16, v3
	v_and_b32_e32 v5, 0xffff0000, v3
	v_div_scale_f32 v8, s[8:9], v6, v6, v10
	v_rcp_f32_e32 v15, v8
	v_rcp_f32_e32 v3, v7
	s_nop 0
	v_mul_f32_e32 v7, v14, v3
	v_fma_f32 v3, -v8, v15, 1.0
	v_fmac_f32_e32 v15, v3, v15
	v_div_scale_f32 v3, vcc, v10, v6, v10
	v_mul_f32_e32 v9, v3, v15
	v_fma_f32 v11, -v8, v9, v3
	v_fmac_f32_e32 v9, v11, v15
	v_rcp_f32_e32 v3, v6
	s_nop 0
	v_mul_f32_e32 v6, v10, v3
	v_pk_mul_f32 v[4:5], v[6:7], v[4:5]
	s_nop 0
	v_cvt_pk_bf16_f32 v3, v4, v5
	v_lshlrev_b64 v[4:5], 12, v[180:181]
	v_lshl_add_u64 v[4:5], v[12:13], 0, v[4:5]
	global_store_dwordx4 v[4:5], v[0:3], off sc1
	s_barrier
	s_cbranch_scc0 .LBB0_414

.LBB0_607:
	s_or_b64 exec, exec, s[6:7]
	s_waitcnt lgkmcnt(0)
	v_ashrrev_i32_e32 v0, 3, v237
	v_add_u32_e32 v0, v0, v238
	v_mul_lo_u32 v1, v0, 48
	v_sub_u32_e32 v12, v230, v1
	v_ashrrev_i32_e32 v1, 31, v0
	v_lshl_add_u64 v[10:11], s[12:13], 0, v[0:1]
	v_mov_b64_e32 v[8:9], s[42:43]
	v_mad_u64_u32 v[4:5], s[6:7], v10, s70, v[8:9]
	v_mov_b32_e32 v6, v5
	v_lshlrev_b32_e32 v2, 3, v12
	v_mad_u64_u32 v[6:7], s[6:7], v11, s70, v[6:7]
	s_mul_i32 s56, s16, 0x300
	v_mov_b32_e32 v5, v6
	v_ashrrev_i32_e32 v3, 31, v2
	v_lshl_add_u64 v[4:5], v[4:5], 0, s[56:57]
	v_lshlrev_b64 v[16:17], 1, v[2:3]
	v_lshl_add_u64 v[4:5], v[4:5], 0, v[16:17]
	v_add_co_u32_e32 v4, vcc, s80, v4
	s_nop 1
	v_addc_co_u32_e32 v5, vcc, 0, v5, vcc
	s_barrier
	global_load_dwordx4 v[22:25], v[4:5], off offset:3072 nt
	v_lshl_add_u32 v1, v0, 2, 0
	v_mul_lo_u32 v0, v0, s79
	v_lshlrev_b32_e32 v4, 4, v12
	v_add3_u32 v0, v1, v0, v4
	s_load_dwordx2 s[18:19], s[0:1], 0x38
	ds_read_b128 v[26:29], v0 offset:63488
	ds_read2st64_b32 v[18:19], v1 offset0:16 offset1:17
	ds_read2st64_b32 v[14:15], v1 offset0:18 offset1:19
	s_add_u32 s16, s71, s56
	s_addc_u32 s17, s72, 0
	s_waitcnt lgkmcnt(0)
	v_lshlrev_b32_e32 v12, 16, v26
	v_and_b32_e32 v13, 0xffff0000, v26
	v_lshlrev_b32_e32 v20, 16, v27
	v_and_b32_e32 v21, 0xffff0000, v27
	v_lshl_add_u64 v[4:5], v[2:3], 2, s[18:19]
	global_load_dwordx4 v[0:3], v[4:5], off offset:16
	s_nop 0
	global_load_dwordx4 v[4:7], v[4:5], off
	v_lshlrev_b64 v[10:11], 12, v[10:11]
	v_lshl_add_u64 v[10:11], s[16:17], 0, v[10:11]
	v_lshl_add_u64 v[16:17], v[10:11], 0, v[16:17]
	s_add_i32 s3, s3, s73
	s_waitcnt vmcnt(2)
	v_lshlrev_b32_e32 v30, 16, v22
	v_and_b32_e32 v31, 0xffff0000, v22
	v_lshlrev_b32_e32 v32, 16, v23
	v_and_b32_e32 v33, 0xffff0000, v23
	v_mul_f32_e32 v22, 0xbfb8aa3b, v30
	v_mul_f32_e32 v23, 0xbfb8aa3b, v31
	v_exp_f32_e32 v22, v22
	v_exp_f32_e32 v23, v23
	v_mul_f32_e32 v26, 0xbfb8aa3b, v32
	v_mul_f32_e32 v27, 0xbfb8aa3b, v33
	v_exp_f32_e32 v26, v26
	v_exp_f32_e32 v27, v27
	v_pk_add_f32 v[22:23], v[22:23], 1.0 op_sel_hi:[1,0]
	v_lshlrev_b32_e32 v34, 16, v24
	v_div_scale_f32 v36, s[6:7], v23, v23, v31
	v_pk_add_f32 v[26:27], v[26:27], 1.0 op_sel_hi:[1,0]
	v_div_scale_f32 v38, s[6:7], v22, v22, v30
	v_rcp_f32_e32 v44, v36
	v_div_scale_f32 v40, s[8:9], v27, v27, v33
	v_rcp_f32_e32 v45, v38
	v_rcp_f32_e32 v46, v40
	v_fma_f32 v120, -v36, v44, 1.0
	v_div_scale_f32 v37, vcc, v31, v23, v31
	v_fma_f32 v121, -v38, v45, 1.0
	v_fmac_f32_e32 v44, v120, v44
	v_div_scale_f32 v39, s[6:7], v30, v22, v30
	v_fma_f32 v122, -v40, v46, 1.0
	v_fmac_f32_e32 v45, v121, v45
	v_mul_f32_e32 v120, v37, v44
	v_div_scale_f32 v41, s[8:9], v33, v27, v33
	v_fmac_f32_e32 v46, v122, v46
	v_mul_f32_e32 v121, v39, v45
	v_fma_f32 v124, -v36, v120, v37
	v_mul_f32_e32 v122, v41, v46
	v_fma_f32 v125, -v38, v121, v39
	v_fmac_f32_e32 v120, v124, v44
	v_fma_f32 v126, -v40, v122, v41
	v_fmac_f32_e32 v121, v125, v45
	v_fmac_f32_e32 v122, v126, v46
	s_mov_b64 vcc, s[6:7]
	v_and_b32_e32 v24, 0xffff0000, v24
	v_div_scale_f32 v42, s[10:11], v26, v26, v32
	v_rcp_f32_e32 v36, v23
	s_nop 0
	v_mul_f32_e32 v23, v31, v36
	s_mov_b64 vcc, s[8:9]
	v_mul_f32_e32 v35, 0xbfb8aa3b, v34
	v_rcp_f32_e32 v47, v42
	v_rcp_f32_e32 v31, v22
	s_nop 0
	v_mul_f32_e32 v22, v30, v31
	v_mul_f32_e32 v31, 0xbfb8aa3b, v24
	v_rcp_f32_e32 v30, v27
	s_nop 0
	v_mul_f32_e32 v27, v33, v30
	v_exp_f32_e32 v30, v35
	v_exp_f32_e32 v31, v31
	v_fma_f32 v123, -v42, v47, 1.0
	v_div_scale_f32 v43, s[10:11], v32, v26, v32
	v_fmac_f32_e32 v47, v123, v47
	v_pk_add_f32 v[30:31], v[30:31], 1.0 op_sel_hi:[1,0]
	v_mul_f32_e32 v123, v43, v47
	v_fma_f32 v127, -v42, v123, v43
	v_fmac_f32_e32 v123, v127, v47
	s_mov_b64 vcc, s[10:11]
	v_rcp_f32_e32 v33, v26
	s_nop 0
	v_mul_f32_e32 v26, v32, v33
	v_lshlrev_b32_e32 v32, 16, v28
	v_and_b32_e32 v33, 0xffff0000, v28
	v_rcp_f32_e32 v28, v31
	s_nop 0
	v_mul_f32_e32 v31, v24, v28
	v_lshlrev_b32_e32 v37, 16, v25
	v_and_b32_e32 v39, 0xffff0000, v25
	v_mul_f32_e32 v24, 0xbfb8aa3b, v37
	v_mul_f32_e32 v25, 0xbfb8aa3b, v39
	v_exp_f32_e32 v24, v24
	v_exp_f32_e32 v25, v25
	v_rcp_f32_e32 v28, v30
	s_nop 0
	v_mul_f32_e32 v30, v34, v28
	v_pk_add_f32 v[24:25], v[24:25], 1.0 op_sel_hi:[1,0]
	v_lshlrev_b32_e32 v28, 16, v29
	v_and_b32_e32 v29, 0xffff0000, v29
	v_rcp_f32_e32 v34, v25
	s_nop 0
	v_mul_f32_e32 v25, v39, v34
	v_mov_b32_e32 v39, v18
	v_div_scale_f32 v34, vcc, v37, v24, v37
	v_rcp_f32_e32 v34, v24
	s_nop 0
	v_mul_f32_e32 v24, v37, v34
	v_ashrrev_i32_e32 v34, 3, v235
	v_add_u32_e32 v34, v34, v236
	v_lshl_add_u32 v40, v34, 2, 0
	ds_read2st64_b32 v[36:37], v40 offset0:16 offset1:17
	ds_read2st64_b32 v[10:11], v40 offset0:18 offset1:19
	v_mul_lo_u32 v35, v34, 48
	s_waitcnt lgkmcnt(1)
	v_mov_b32_e32 v38, v36
	v_mov_b32_e32 v18, v37
	v_pk_add_f32 v[18:19], v[38:39], v[18:19]
	s_waitcnt lgkmcnt(0)
	v_mov_b32_e32 v36, v10
	v_mov_b32_e32 v37, v14
	v_pk_add_f32 v[18:19], v[18:19], v[36:37]
	v_mov_b32_e32 v14, v11
	v_pk_add_f32 v[14:15], v[18:19], v[14:15]
	v_mov_b64_e32 v[10:11], s[66:67]
	v_pk_fma_f32 v[36:37], v[14:15], s[64:65], v[10:11] op_sel_hi:[1,0,0]
	s_nop 0
	v_mul_f32_e32 v14, 0x4b800000, v37
	v_cmp_gt_f32_e32 vcc, s81, v37
	s_nop 1
	v_cndmask_b32_e32 v14, v37, v14, vcc
	v_rsq_f32_e32 v15, v14
	v_sub_u32_e32 v37, v234, v35
	v_ashrrev_i32_e32 v35, 31, v34
	v_lshlrev_b32_e32 v14, 3, v37
	v_mul_f32_e32 v18, 0x45800000, v15
	v_cndmask_b32_e32 v18, v15, v18, vcc
	v_pk_mul_f32 v[12:13], v[18:19], v[12:13] op_sel_hi:[0,1]
	s_waitcnt vmcnt(0)
	v_pk_mul_f32 v[4:5], v[4:5], v[12:13]
	v_pk_mul_f32 v[12:13], v[18:19], v[20:21] op_sel_hi:[0,1]
	v_pk_mul_f32 v[6:7], v[6:7], v[12:13]
	v_pk_mul_f32 v[4:5], v[22:23], v[4:5]
	v_pk_mul_f32 v[6:7], v[26:27], v[6:7]
	v_cvt_pk_bf16_f32 v4, v4, v5
	v_cvt_pk_bf16_f32 v5, v6, v7
	v_pk_mul_f32 v[6:7], v[18:19], v[32:33] op_sel_hi:[0,1]
	v_pk_mul_f32 v[0:1], v[0:1], v[6:7]
	v_ashrrev_i32_e32 v15, 31, v14
	v_pk_mul_f32 v[0:1], v[30:31], v[0:1]
	v_mul_f32_e32 v20, 0x4b800000, v36
	v_cvt_pk_bf16_f32 v6, v0, v1
	v_pk_mul_f32 v[0:1], v[18:19], v[28:29] op_sel_hi:[0,1]
	v_pk_mul_f32 v[0:1], v[2:3], v[0:1]
	v_lshlrev_b32_e32 v21, 4, v37
	v_pk_mul_f32 v[0:1], v[24:25], v[0:1]
	s_nop 0
	v_cvt_pk_bf16_f32 v7, v0, v1
	v_lshl_add_u64 v[0:1], s[12:13], 0, v[34:35]
	v_mad_u64_u32 v[2:3], s[6:7], v0, s70, v[8:9]
	global_store_dwordx4 v[16:17], v[4:7], off sc1
	v_lshl_add_u64 v[16:17], v[14:15], 2, s[18:19]
	s_nop 0
	v_mov_b32_e32 v4, v3
	v_mad_u64_u32 v[4:5], s[6:7], v1, s70, v[4:5]
	v_mov_b32_e32 v3, v4
	v_lshl_add_u64 v[2:3], v[2:3], 0, s[56:57]
	v_lshlrev_b64 v[6:7], 1, v[14:15]
	v_lshl_add_u64 v[2:3], v[2:3], 0, v[6:7]
	v_add_co_u32_e32 v2, vcc, s80, v2
	v_lshlrev_b64 v[0:1], 12, v[0:1]
	s_nop 0
	v_addc_co_u32_e32 v3, vcc, 0, v3, vcc
	global_load_dwordx4 v[2:5], v[2:3], off offset:3072 nt
	s_nop 0
	global_load_dwordx4 v[12:15], v[16:17], off
	s_nop 0
	global_load_dwordx4 v[16:19], v[16:17], off offset:16
	v_cmp_gt_f32_e32 vcc, s81, v36
	v_lshl_add_u64 v[0:1], s[16:17], 0, v[0:1]
	v_lshl_add_u64 v[0:1], v[0:1], 0, v[6:7]
	v_cndmask_b32_e32 v20, v36, v20, vcc
	v_rsq_f32_e32 v26, v20
	v_mul_lo_u32 v20, v34, s79
	v_add3_u32 v20, v40, v20, v21
	ds_read_b128 v[20:23], v20 offset:63488
	v_mul_f32_e32 v28, 0x45800000, v26
	v_cndmask_b32_e32 v26, v26, v28, vcc
	s_waitcnt lgkmcnt(0)
	v_lshlrev_b32_e32 v28, 16, v20
	v_and_b32_e32 v29, 0xffff0000, v20
	s_waitcnt vmcnt(2)
	v_lshlrev_b32_e32 v27, 16, v2
	v_and_b32_e32 v2, 0xffff0000, v2
	v_mul_f32_e32 v24, 0xbfb8aa3b, v27
	v_mul_f32_e32 v25, 0xbfb8aa3b, v2
	v_exp_f32_e32 v24, v24
	v_exp_f32_e32 v25, v25
	v_pk_mul_f32 v[28:29], v[26:27], v[28:29] op_sel_hi:[0,1]
	s_waitcnt vmcnt(1)
	v_pk_mul_f32 v[12:13], v[12:13], v[28:29]
	v_pk_add_f32 v[24:25], v[24:25], 1.0 op_sel_hi:[1,0]
	s_nop 0
	s_nop 0
	v_rcp_f32_e32 v20, v25
	s_nop 0
	v_mul_f32_e32 v25, v2, v20
	v_lshlrev_b32_e32 v20, 16, v3
	v_rcp_f32_e32 v2, v24
	s_nop 0
	v_mul_f32_e32 v24, v27, v2
	v_and_b32_e32 v27, 0xffff0000, v3
	v_mul_f32_e32 v2, 0xbfb8aa3b, v20
	v_exp_f32_e32 v28, v2
	v_mul_f32_e32 v2, 0xbfb8aa3b, v27
	v_exp_f32_e32 v29, v2
	v_pk_mul_f32 v[2:3], v[24:25], v[12:13]
	v_lshlrev_b32_e32 v12, 16, v21
	v_cvt_pk_bf16_f32 v2, v2, v3
	v_pk_add_f32 v[24:25], v[28:29], 1.0 op_sel_hi:[1,0]
	v_and_b32_e32 v13, 0xffff0000, v21
	v_pk_mul_f32 v[12:13], v[26:27], v[12:13] op_sel_hi:[0,1]
	v_pk_mul_f32 v[12:13], v[14:15], v[12:13]
	v_div_scale_f32 v14, s[6:7], v24, v24, v20
	v_rcp_f32_e32 v21, v14
	v_rcp_f32_e32 v3, v25
	s_nop 0
	v_mul_f32_e32 v15, v27, v3
	v_fma_f32 v3, -v14, v21, 1.0
	v_fmac_f32_e32 v21, v3, v21
	v_div_scale_f32 v3, vcc, v20, v24, v20
	v_mul_f32_e32 v25, v3, v21
	v_fma_f32 v27, -v14, v25, v3
	v_rcp_f32_e32 v3, v24
	s_nop 0
	v_mul_f32_e32 v14, v20, v3
	v_lshlrev_b32_e32 v24, 16, v4
	v_and_b32_e32 v4, 0xffff0000, v4
	v_mul_f32_e32 v3, 0xbfb8aa3b, v24
	v_exp_f32_e32 v20, v3
	v_mul_f32_e32 v3, 0xbfb8aa3b, v4
	v_exp_f32_e32 v21, v3
	v_pk_mul_f32 v[12:13], v[14:15], v[12:13]
	v_pk_add_f32 v[14:15], v[20:21], 1.0 op_sel_hi:[1,0]
	s_nop 0
	v_cvt_pk_bf16_f32 v3, v12, v13
	v_lshlrev_b32_e32 v12, 16, v22
	v_and_b32_e32 v13, 0xffff0000, v22
	v_pk_mul_f32 v[12:13], v[26:27], v[12:13] op_sel_hi:[0,1]
	s_waitcnt vmcnt(0)
	v_pk_mul_f32 v[12:13], v[16:17], v[12:13]
	v_rcp_f32_e32 v16, v15
	s_nop 0
	v_mul_f32_e32 v15, v4, v16
	v_and_b32_e32 v21, 0xffff0000, v5
	v_lshlrev_b32_e32 v20, 16, v5
	v_rcp_f32_e32 v4, v14
	s_nop 0
	v_mul_f32_e32 v14, v24, v4
	v_mul_f32_e32 v4, 0xbfb8aa3b, v20
	v_exp_f32_e32 v16, v4
	v_mul_f32_e32 v4, 0xbfb8aa3b, v21
	v_exp_f32_e32 v17, v4
	v_pk_mul_f32 v[4:5], v[14:15], v[12:13]
	v_lshlrev_b32_e32 v12, 16, v23
	v_cvt_pk_bf16_f32 v4, v4, v5
	v_pk_add_f32 v[14:15], v[16:17], 1.0 op_sel_hi:[1,0]
	v_and_b32_e32 v13, 0xffff0000, v23
	v_pk_mul_f32 v[12:13], v[26:27], v[12:13] op_sel_hi:[0,1]
	v_pk_mul_f32 v[12:13], v[18:19], v[12:13]
	v_rcp_f32_e32 v5, v15
	s_nop 0
	v_mul_f32_e32 v15, v21, v5
	v_rcp_f32_e32 v5, v14
	s_nop 0
	v_mul_f32_e32 v14, v20, v5
	v_pk_mul_f32 v[12:13], v[14:15], v[12:13]
	s_nop 0
	v_cvt_pk_bf16_f32 v5, v12, v13
	global_store_dwordx4 v[0:1], v[2:5], off sc1
	v_ashrrev_i32_e32 v0, 3, v232
	v_add_u32_e32 v0, v0, v233
	v_mul_lo_u32 v1, v0, 48
	v_sub_u32_e32 v12, v231, v1
	v_ashrrev_i32_e32 v1, 31, v0
	v_lshl_add_u64 v[20:21], s[12:13], 0, v[0:1]
	v_mad_u64_u32 v[4:5], s[6:7], v20, s70, v[8:9]
	v_mov_b32_e32 v6, v5
	v_lshlrev_b32_e32 v2, 3, v12
	v_mad_u64_u32 v[6:7], s[6:7], v21, s70, v[6:7]
	v_mov_b32_e32 v5, v6
	v_ashrrev_i32_e32 v3, 31, v2
	v_lshl_add_u64 v[4:5], v[4:5], 0, s[56:57]
	v_lshlrev_b64 v[22:23], 1, v[2:3]
	v_lshl_add_u64 v[4:5], v[4:5], 0, v[22:23]
	v_add_co_u32_e32 v4, vcc, s80, v4
	v_lshl_add_u32 v13, v0, 2, 0
	s_nop 0
	v_addc_co_u32_e32 v5, vcc, 0, v5, vcc
	global_load_dwordx4 v[4:7], v[4:5], off offset:3072 nt
	v_mul_lo_u32 v14, v0, s79
	v_lshlrev_b32_e32 v12, 4, v12
	v_add3_u32 v12, v13, v14, v12
	ds_read2st64_b32 v[24:25], v13 offset0:16 offset1:17
	ds_read2st64_b32 v[26:27], v13 offset0:18 offset1:19
	ds_read_b128 v[12:15], v12 offset:63488
	v_lshl_add_u64 v[16:17], v[2:3], 2, s[18:19]
	s_waitcnt lgkmcnt(0)
	v_lshlrev_b32_e32 v30, 16, v12
	v_and_b32_e32 v31, 0xffff0000, v12
	s_waitcnt vmcnt(0)
	v_lshlrev_b32_e32 v32, 16, v4
	v_and_b32_e32 v4, 0xffff0000, v4
	v_mul_f32_e32 v0, 0xbfb8aa3b, v32
	v_mul_f32_e32 v1, 0xbfb8aa3b, v4
	v_exp_f32_e32 v0, v0
	v_exp_f32_e32 v1, v1
	v_lshlrev_b32_e32 v37, 16, v5
	v_lshlrev_b32_e32 v40, 16, v6
	v_and_b32_e32 v6, 0xffff0000, v6
	v_pk_add_f32 v[28:29], v[0:1], 1.0 op_sel_hi:[1,0]
	global_load_dwordx4 v[0:3], v[16:17], off offset:16
	s_nop 0
	global_load_dwordx4 v[16:19], v[16:17], off
	v_lshlrev_b32_e32 v41, 16, v7
	v_and_b32_e32 v7, 0xffff0000, v7
	v_rcp_f32_e32 v12, v29
	s_nop 0
	v_mul_f32_e32 v29, v4, v12
	v_and_b32_e32 v35, 0xffff0000, v5
	v_mul_f32_e32 v4, 0xbfb8aa3b, v37
	v_mul_f32_e32 v5, 0xbfb8aa3b, v35
	v_exp_f32_e32 v4, v4
	v_exp_f32_e32 v5, v5
	v_rcp_f32_e32 v12, v28
	s_nop 0
	v_mul_f32_e32 v28, v32, v12
	v_pk_add_f32 v[4:5], v[4:5], 1.0 op_sel_hi:[1,0]
	v_lshlrev_b32_e32 v12, 16, v13
	v_and_b32_e32 v13, 0xffff0000, v13
	v_rcp_f32_e32 v32, v5
	s_nop 0
	v_mul_f32_e32 v33, v35, v32
	v_mul_f32_e32 v34, 0xbfb8aa3b, v40
	v_mul_f32_e32 v35, 0xbfb8aa3b, v6
	v_exp_f32_e32 v34, v34
	v_exp_f32_e32 v35, v35
	v_rcp_f32_e32 v5, v4
	s_nop 0
	v_mul_f32_e32 v32, v37, v5
	v_pk_add_f32 v[34:35], v[34:35], 1.0 op_sel_hi:[1,0]
	v_lshlrev_b32_e32 v36, 16, v14
	v_and_b32_e32 v37, 0xffff0000, v14
	v_rcp_f32_e32 v4, v35
	s_nop 0
	v_mul_f32_e32 v35, v6, v4
	v_mul_f32_e32 v4, 0xbfb8aa3b, v41
	v_mul_f32_e32 v5, 0xbfb8aa3b, v7
	v_exp_f32_e32 v4, v4
	v_exp_f32_e32 v5, v5
	v_rcp_f32_e32 v6, v34
	s_nop 0
	v_mul_f32_e32 v34, v40, v6
	v_pk_add_f32 v[4:5], v[4:5], 1.0 op_sel_hi:[1,0]
	v_lshlrev_b32_e32 v14, 16, v15
	v_and_b32_e32 v15, 0xffff0000, v15
	v_rcp_f32_e32 v6, v5
	s_nop 0
	v_mul_f32_e32 v39, v7, v6
	v_div_scale_f32 v5, vcc, v41, v4, v41
	v_rcp_f32_e32 v5, v4
	s_nop 0
	v_mul_f32_e32 v38, v41, v5
	v_lshlrev_b64 v[4:5], 12, v[20:21]
	v_add_u32_e32 v21, 0x600, v230
	v_mul_hi_i32 v6, v21, s74
	v_lshrrev_b32_e32 v7, 31, v6
	v_ashrrev_i32_e32 v6, 3, v6
	v_add_u32_e32 v20, v6, v7
	v_lshl_add_u32 v42, v20, 2, 0
	ds_read2st64_b32 v[6:7], v42 offset0:16 offset1:17
	v_lshl_add_u64 v[4:5], s[16:17], 0, v[4:5]
	v_lshl_add_u64 v[22:23], v[4:5], 0, v[22:23]
	ds_read2st64_b32 v[4:5], v42 offset0:18 offset1:19
	v_mov_b32_e32 v41, v24
	s_waitcnt lgkmcnt(1)
	v_mov_b32_e32 v40, v6
	v_mov_b32_e32 v24, v7
	v_pk_add_f32 v[6:7], v[40:41], v[24:25]
	s_waitcnt lgkmcnt(0)
	v_mov_b32_e32 v24, v4
	v_mov_b32_e32 v25, v26
	v_pk_add_f32 v[6:7], v[6:7], v[24:25]
	v_mov_b32_e32 v26, v5
	v_pk_add_f32 v[4:5], v[6:7], v[26:27]
	v_mul_lo_u32 v43, v20, 48
	v_pk_fma_f32 v[24:25], v[4:5], s[64:65], v[10:11] op_sel_hi:[1,0,0]
	s_nop 0
	v_mul_f32_e32 v4, 0x4b800000, v25
	v_cmp_gt_f32_e32 vcc, s81, v25
	s_nop 1
	v_cndmask_b32_e32 v4, v25, v4, vcc
	v_rsq_f32_e32 v4, v4
	v_sub_u32_e32 v25, v21, v43
	v_ashrrev_i32_e32 v21, 31, v20
	v_lshlrev_b32_e32 v26, 3, v25
	v_mul_f32_e32 v5, 0x45800000, v4
	v_cndmask_b32_e32 v40, v4, v5, vcc
	v_pk_mul_f32 v[4:5], v[40:41], v[30:31] op_sel_hi:[0,1]
	v_pk_mul_f32 v[6:7], v[40:41], v[12:13] op_sel_hi:[0,1]
	s_waitcnt vmcnt(0)
	v_pk_mul_f32 v[4:5], v[16:17], v[4:5]
	v_pk_mul_f32 v[6:7], v[18:19], v[6:7]
	v_pk_mul_f32 v[4:5], v[28:29], v[4:5]
	v_pk_mul_f32 v[6:7], v[32:33], v[6:7]
	v_cvt_pk_bf16_f32 v4, v4, v5
	v_cvt_pk_bf16_f32 v5, v6, v7
	v_pk_mul_f32 v[6:7], v[40:41], v[36:37] op_sel_hi:[0,1]
	v_pk_mul_f32 v[0:1], v[0:1], v[6:7]
	v_ashrrev_i32_e32 v27, 31, v26
	v_pk_mul_f32 v[0:1], v[34:35], v[0:1]
	v_lshl_add_u64 v[16:17], v[26:27], 2, s[18:19]
	v_cvt_pk_bf16_f32 v6, v0, v1
	v_pk_mul_f32 v[0:1], v[40:41], v[14:15] op_sel_hi:[0,1]
	v_pk_mul_f32 v[0:1], v[2:3], v[0:1]
	s_nop 0
	v_pk_mul_f32 v[0:1], v[38:39], v[0:1]
	s_nop 0
	v_cvt_pk_bf16_f32 v7, v0, v1
	v_lshl_add_u64 v[0:1], s[12:13], 0, v[20:21]
	v_mad_u64_u32 v[2:3], s[6:7], v0, s70, v[8:9]
	global_store_dwordx4 v[22:23], v[4:7], off sc1
	v_mul_f32_e32 v21, 0x4b800000, v24
	v_mul_lo_u32 v20, v20, s79
	v_mov_b32_e32 v4, v3
	v_mad_u64_u32 v[4:5], s[6:7], v1, s70, v[4:5]
	v_mov_b32_e32 v3, v4
	v_lshl_add_u64 v[2:3], v[2:3], 0, s[56:57]
	v_lshlrev_b64 v[6:7], 1, v[26:27]
	v_lshl_add_u64 v[2:3], v[2:3], 0, v[6:7]
	v_add_co_u32_e32 v2, vcc, s80, v2
	v_lshlrev_b64 v[0:1], 12, v[0:1]
	s_nop 0
	v_addc_co_u32_e32 v3, vcc, 0, v3, vcc
	global_load_dwordx4 v[2:5], v[2:3], off offset:3072 nt
	s_nop 0
	global_load_dwordx4 v[12:15], v[16:17], off
	s_nop 0
	global_load_dwordx4 v[16:19], v[16:17], off offset:16
	v_cmp_gt_f32_e32 vcc, s81, v24
	v_lshl_add_u64 v[0:1], s[16:17], 0, v[0:1]
	v_lshl_add_u64 v[0:1], v[0:1], 0, v[6:7]
	v_cndmask_b32_e32 v21, v24, v21, vcc
	v_rsq_f32_e32 v26, v21
	v_lshlrev_b32_e32 v21, 4, v25
	v_add3_u32 v20, v42, v20, v21
	ds_read_b128 v[20:23], v20 offset:63488
	v_mul_f32_e32 v28, 0x45800000, v26
	v_cndmask_b32_e32 v26, v26, v28, vcc
	s_waitcnt lgkmcnt(0)
	v_lshlrev_b32_e32 v28, 16, v20
	v_and_b32_e32 v29, 0xffff0000, v20
	s_waitcnt vmcnt(2)
	v_lshlrev_b32_e32 v27, 16, v2
	v_and_b32_e32 v2, 0xffff0000, v2
	v_mul_f32_e32 v24, 0xbfb8aa3b, v27
	v_mul_f32_e32 v25, 0xbfb8aa3b, v2
	v_exp_f32_e32 v24, v24
	v_exp_f32_e32 v25, v25
	v_pk_mul_f32 v[28:29], v[26:27], v[28:29] op_sel_hi:[0,1]
	s_waitcnt vmcnt(1)
	v_pk_mul_f32 v[12:13], v[12:13], v[28:29]
	v_pk_add_f32 v[24:25], v[24:25], 1.0 op_sel_hi:[1,0]
	s_nop 0
	s_nop 0
	v_rcp_f32_e32 v20, v25
	s_nop 0
	v_mul_f32_e32 v25, v2, v20
	v_lshlrev_b32_e32 v20, 16, v3
	v_rcp_f32_e32 v2, v24
	s_nop 0
	v_mul_f32_e32 v24, v27, v2
	v_and_b32_e32 v27, 0xffff0000, v3
	v_mul_f32_e32 v2, 0xbfb8aa3b, v20
	v_exp_f32_e32 v28, v2
	v_mul_f32_e32 v2, 0xbfb8aa3b, v27
	v_exp_f32_e32 v29, v2
	v_pk_mul_f32 v[2:3], v[24:25], v[12:13]
	v_lshlrev_b32_e32 v12, 16, v21
	v_cvt_pk_bf16_f32 v2, v2, v3
	v_pk_add_f32 v[24:25], v[28:29], 1.0 op_sel_hi:[1,0]
	v_and_b32_e32 v13, 0xffff0000, v21
	v_pk_mul_f32 v[12:13], v[26:27], v[12:13] op_sel_hi:[0,1]
	v_pk_mul_f32 v[12:13], v[14:15], v[12:13]
	v_div_scale_f32 v14, s[6:7], v24, v24, v20
	v_rcp_f32_e32 v21, v14
	v_rcp_f32_e32 v3, v25
	s_nop 0
	v_mul_f32_e32 v15, v27, v3
	v_fma_f32 v3, -v14, v21, 1.0
	v_fmac_f32_e32 v21, v3, v21
	v_div_scale_f32 v3, vcc, v20, v24, v20
	v_mul_f32_e32 v25, v3, v21
	v_fma_f32 v27, -v14, v25, v3
	v_rcp_f32_e32 v3, v24
	s_nop 0
	v_mul_f32_e32 v14, v20, v3
	v_lshlrev_b32_e32 v24, 16, v4
	v_and_b32_e32 v4, 0xffff0000, v4
	v_mul_f32_e32 v3, 0xbfb8aa3b, v24
	v_exp_f32_e32 v20, v3
	v_mul_f32_e32 v3, 0xbfb8aa3b, v4
	v_exp_f32_e32 v21, v3
	v_pk_mul_f32 v[12:13], v[14:15], v[12:13]
	v_pk_add_f32 v[14:15], v[20:21], 1.0 op_sel_hi:[1,0]
	s_nop 0
	v_cvt_pk_bf16_f32 v3, v12, v13
	v_lshlrev_b32_e32 v12, 16, v22
	v_and_b32_e32 v13, 0xffff0000, v22
	v_pk_mul_f32 v[12:13], v[26:27], v[12:13] op_sel_hi:[0,1]
	s_waitcnt vmcnt(0)
	v_pk_mul_f32 v[12:13], v[16:17], v[12:13]
	v_rcp_f32_e32 v16, v15
	s_nop 0
	v_mul_f32_e32 v15, v4, v16
	v_and_b32_e32 v21, 0xffff0000, v5
	v_lshlrev_b32_e32 v20, 16, v5
	v_rcp_f32_e32 v4, v14
	s_nop 0
	v_mul_f32_e32 v14, v24, v4
	v_mul_f32_e32 v4, 0xbfb8aa3b, v20
	v_exp_f32_e32 v16, v4
	v_mul_f32_e32 v4, 0xbfb8aa3b, v21
	v_exp_f32_e32 v17, v4
	v_pk_mul_f32 v[4:5], v[14:15], v[12:13]
	v_lshlrev_b32_e32 v12, 16, v23
	v_cvt_pk_bf16_f32 v4, v4, v5
	v_pk_add_f32 v[14:15], v[16:17], 1.0 op_sel_hi:[1,0]
	v_and_b32_e32 v13, 0xffff0000, v23
	v_pk_mul_f32 v[12:13], v[26:27], v[12:13] op_sel_hi:[0,1]
	v_pk_mul_f32 v[12:13], v[18:19], v[12:13]
	v_rcp_f32_e32 v5, v15
	s_nop 0
	v_mul_f32_e32 v15, v21, v5
	v_rcp_f32_e32 v5, v14
	s_nop 0
	v_mul_f32_e32 v14, v20, v5
	v_pk_mul_f32 v[12:13], v[14:15], v[12:13]
	s_nop 0
	v_cvt_pk_bf16_f32 v5, v12, v13
	global_store_dwordx4 v[0:1], v[2:5], off sc1
	v_add_u32_e32 v1, 0x800, v230
	v_mul_hi_i32 v0, v1, s74
	v_lshrrev_b32_e32 v2, 31, v0
	v_ashrrev_i32_e32 v0, 3, v0
	v_add_u32_e32 v0, v0, v2
	v_mul_lo_u32 v2, v0, 48
	v_sub_u32_e32 v12, v1, v2
	v_ashrrev_i32_e32 v1, 31, v0
	v_lshl_add_u64 v[20:21], s[12:13], 0, v[0:1]
	v_mad_u64_u32 v[4:5], s[6:7], v20, s70, v[8:9]
	v_mov_b32_e32 v6, v5
	v_lshlrev_b32_e32 v2, 3, v12
	v_mad_u64_u32 v[6:7], s[6:7], v21, s70, v[6:7]
	v_mov_b32_e32 v5, v6
	v_ashrrev_i32_e32 v3, 31, v2
	v_lshl_add_u64 v[4:5], v[4:5], 0, s[56:57]
	v_lshlrev_b64 v[22:23], 1, v[2:3]
	v_lshl_add_u64 v[4:5], v[4:5], 0, v[22:23]
	v_add_co_u32_e32 v4, vcc, s80, v4
	v_lshl_add_u32 v13, v0, 2, 0
	s_nop 0
	v_addc_co_u32_e32 v5, vcc, 0, v5, vcc
	global_load_dwordx4 v[4:7], v[4:5], off offset:3072 nt
	v_mul_lo_u32 v14, v0, s79
	v_lshlrev_b32_e32 v12, 4, v12
	v_add3_u32 v12, v13, v14, v12
	ds_read2st64_b32 v[24:25], v13 offset0:16 offset1:17
	ds_read2st64_b32 v[26:27], v13 offset0:18 offset1:19
	ds_read_b128 v[12:15], v12 offset:63488
	v_lshl_add_u64 v[16:17], v[2:3], 2, s[18:19]
	s_waitcnt lgkmcnt(0)
	v_lshlrev_b32_e32 v30, 16, v12
	v_and_b32_e32 v31, 0xffff0000, v12
	s_waitcnt vmcnt(0)
	v_lshlrev_b32_e32 v32, 16, v4
	v_and_b32_e32 v4, 0xffff0000, v4
	v_mul_f32_e32 v0, 0xbfb8aa3b, v32
	v_mul_f32_e32 v1, 0xbfb8aa3b, v4
	v_exp_f32_e32 v0, v0
	v_exp_f32_e32 v1, v1
	v_lshlrev_b32_e32 v37, 16, v5
	v_lshlrev_b32_e32 v40, 16, v6
	v_and_b32_e32 v6, 0xffff0000, v6
	v_pk_add_f32 v[28:29], v[0:1], 1.0 op_sel_hi:[1,0]
	global_load_dwordx4 v[0:3], v[16:17], off offset:16
	s_nop 0
	global_load_dwordx4 v[16:19], v[16:17], off
	v_lshlrev_b32_e32 v41, 16, v7
	v_and_b32_e32 v7, 0xffff0000, v7
	v_rcp_f32_e32 v12, v29
	s_nop 0
	v_mul_f32_e32 v29, v4, v12
	v_and_b32_e32 v35, 0xffff0000, v5
	v_mul_f32_e32 v4, 0xbfb8aa3b, v37
	v_mul_f32_e32 v5, 0xbfb8aa3b, v35
	v_exp_f32_e32 v4, v4
	v_exp_f32_e32 v5, v5
	v_rcp_f32_e32 v12, v28
	s_nop 0
	v_mul_f32_e32 v28, v32, v12
	v_pk_add_f32 v[4:5], v[4:5], 1.0 op_sel_hi:[1,0]
	v_lshlrev_b32_e32 v12, 16, v13
	v_and_b32_e32 v13, 0xffff0000, v13
	v_rcp_f32_e32 v32, v5
	s_nop 0
	v_mul_f32_e32 v33, v35, v32
	v_mul_f32_e32 v34, 0xbfb8aa3b, v40
	v_mul_f32_e32 v35, 0xbfb8aa3b, v6
	v_exp_f32_e32 v34, v34
	v_exp_f32_e32 v35, v35
	v_rcp_f32_e32 v5, v4
	s_nop 0
	v_mul_f32_e32 v32, v37, v5
	v_pk_add_f32 v[34:35], v[34:35], 1.0 op_sel_hi:[1,0]
	v_lshlrev_b32_e32 v36, 16, v14
	v_and_b32_e32 v37, 0xffff0000, v14
	v_rcp_f32_e32 v4, v35
	s_nop 0
	v_mul_f32_e32 v35, v6, v4
	v_mul_f32_e32 v4, 0xbfb8aa3b, v41
	v_mul_f32_e32 v5, 0xbfb8aa3b, v7
	v_exp_f32_e32 v4, v4
	v_exp_f32_e32 v5, v5
	v_rcp_f32_e32 v6, v34
	s_nop 0
	v_mul_f32_e32 v34, v40, v6
	v_pk_add_f32 v[4:5], v[4:5], 1.0 op_sel_hi:[1,0]
	v_lshlrev_b32_e32 v14, 16, v15
	v_and_b32_e32 v15, 0xffff0000, v15
	v_rcp_f32_e32 v6, v5
	s_nop 0
	v_mul_f32_e32 v39, v7, v6
	v_div_scale_f32 v5, vcc, v41, v4, v41
	v_rcp_f32_e32 v5, v4
	s_nop 0
	v_mul_f32_e32 v38, v41, v5
	v_lshlrev_b64 v[4:5], 12, v[20:21]
	v_add_u32_e32 v21, 0xa00, v230
	v_mul_hi_i32 v6, v21, s74
	v_lshrrev_b32_e32 v7, 31, v6
	v_ashrrev_i32_e32 v6, 3, v6
	v_add_u32_e32 v20, v6, v7
	v_lshl_add_u32 v42, v20, 2, 0
	ds_read2st64_b32 v[6:7], v42 offset0:16 offset1:17
	v_lshl_add_u64 v[4:5], s[16:17], 0, v[4:5]
	v_lshl_add_u64 v[22:23], v[4:5], 0, v[22:23]
	ds_read2st64_b32 v[4:5], v42 offset0:18 offset1:19
	v_mov_b32_e32 v41, v24
	s_waitcnt lgkmcnt(1)
	v_mov_b32_e32 v40, v6
	v_mov_b32_e32 v24, v7
	v_pk_add_f32 v[6:7], v[40:41], v[24:25]
	s_waitcnt lgkmcnt(0)
	v_mov_b32_e32 v24, v4
	v_mov_b32_e32 v25, v26
	v_pk_add_f32 v[6:7], v[6:7], v[24:25]
	v_mov_b32_e32 v26, v5
	v_pk_add_f32 v[4:5], v[6:7], v[26:27]
	v_mul_lo_u32 v43, v20, 48
	v_pk_fma_f32 v[24:25], v[4:5], s[64:65], v[10:11] op_sel_hi:[1,0,0]
	s_nop 0
	v_mul_f32_e32 v4, 0x4b800000, v25
	v_cmp_gt_f32_e32 vcc, s81, v25
	s_nop 1
	v_cndmask_b32_e32 v4, v25, v4, vcc
	v_rsq_f32_e32 v4, v4
	v_sub_u32_e32 v25, v21, v43
	v_ashrrev_i32_e32 v21, 31, v20
	v_lshlrev_b32_e32 v10, 3, v25
	v_mul_f32_e32 v5, 0x45800000, v4
	v_cndmask_b32_e32 v26, v4, v5, vcc
	v_pk_mul_f32 v[4:5], v[26:27], v[30:31] op_sel_hi:[0,1]
	v_pk_mul_f32 v[6:7], v[26:27], v[12:13] op_sel_hi:[0,1]
	s_waitcnt vmcnt(0)
	v_pk_mul_f32 v[4:5], v[16:17], v[4:5]
	v_pk_mul_f32 v[6:7], v[18:19], v[6:7]
	v_pk_mul_f32 v[4:5], v[28:29], v[4:5]
	v_pk_mul_f32 v[6:7], v[32:33], v[6:7]
	v_cvt_pk_bf16_f32 v4, v4, v5
	v_cvt_pk_bf16_f32 v5, v6, v7
	v_pk_mul_f32 v[6:7], v[26:27], v[36:37] op_sel_hi:[0,1]
	v_pk_mul_f32 v[0:1], v[0:1], v[6:7]
	v_ashrrev_i32_e32 v11, 31, v10
	v_pk_mul_f32 v[0:1], v[34:35], v[0:1]
	v_lshlrev_b64 v[18:19], 1, v[10:11]
	v_cvt_pk_bf16_f32 v6, v0, v1
	v_pk_mul_f32 v[0:1], v[26:27], v[14:15] op_sel_hi:[0,1]
	v_pk_mul_f32 v[0:1], v[2:3], v[0:1]
	v_lshl_add_u64 v[10:11], v[10:11], 2, s[18:19]
	v_pk_mul_f32 v[0:1], v[38:39], v[0:1]
	v_mul_f32_e32 v14, 0x4b800000, v24
	v_cvt_pk_bf16_f32 v7, v0, v1
	v_lshl_add_u64 v[0:1], s[12:13], 0, v[20:21]
	v_mad_u64_u32 v[2:3], s[6:7], v0, s70, v[8:9]
	global_store_dwordx4 v[22:23], v[4:7], off sc1
	v_lshlrev_b32_e32 v15, 4, v25
	s_nop 0
	v_mov_b32_e32 v4, v3
	v_mad_u64_u32 v[4:5], s[6:7], v1, s70, v[4:5]
	v_mov_b32_e32 v3, v4
	v_lshl_add_u64 v[2:3], v[2:3], 0, s[56:57]
	v_lshl_add_u64 v[2:3], v[2:3], 0, v[18:19]
	v_add_co_u32_e32 v2, vcc, s80, v2
	v_lshlrev_b64 v[0:1], 12, v[0:1]
	s_nop 0
	v_addc_co_u32_e32 v3, vcc, 0, v3, vcc
	global_load_dwordx4 v[2:5], v[2:3], off offset:3072 nt
	s_nop 0
	global_load_dwordx4 v[6:9], v[10:11], off
	s_nop 0
	global_load_dwordx4 v[10:13], v[10:11], off offset:16
	v_cmp_gt_f32_e32 vcc, s81, v24
	v_lshl_add_u64 v[0:1], s[16:17], 0, v[0:1]
	v_lshl_add_u64 v[0:1], v[0:1], 0, v[18:19]
	v_cndmask_b32_e32 v14, v24, v14, vcc
	v_rsq_f32_e32 v22, v14
	v_mul_lo_u32 v14, v20, s79
	v_add3_u32 v14, v42, v14, v15
	ds_read_b128 v[14:17], v14 offset:63488
	v_mul_f32_e32 v24, 0x45800000, v22
	v_cndmask_b32_e32 v22, v22, v24, vcc
	s_waitcnt lgkmcnt(0)
	v_lshlrev_b32_e32 v24, 16, v14
	v_and_b32_e32 v25, 0xffff0000, v14
	s_waitcnt vmcnt(2)
	v_lshlrev_b32_e32 v23, 16, v2
	v_and_b32_e32 v2, 0xffff0000, v2
	v_mul_f32_e32 v20, 0xbfb8aa3b, v23
	v_mul_f32_e32 v21, 0xbfb8aa3b, v2
	v_exp_f32_e32 v20, v20
	v_exp_f32_e32 v21, v21
	v_pk_mul_f32 v[24:25], v[22:23], v[24:25] op_sel_hi:[0,1]
	s_waitcnt vmcnt(1)
	v_pk_mul_f32 v[6:7], v[6:7], v[24:25]
	v_pk_add_f32 v[20:21], v[20:21], 1.0 op_sel_hi:[1,0]
	s_nop 0
	v_div_scale_f32 v26, s[6:7], v21, v21, v2
	v_rcp_f32_e32 v27, v26
	s_nop 0
	v_fma_f32 v14, -v26, v27, 1.0
	v_fmac_f32_e32 v27, v14, v27
	v_div_scale_f32 v25, s[6:7], v20, v20, v23
	v_rcp_f32_e32 v26, v25
	v_rcp_f32_e32 v14, v21
	s_nop 0
	v_mul_f32_e32 v21, v2, v14
	v_fma_f32 v2, -v25, v26, 1.0
	v_fmac_f32_e32 v26, v2, v26
	v_lshlrev_b32_e32 v14, 16, v3
	v_rcp_f32_e32 v2, v20
	s_nop 0
	v_mul_f32_e32 v20, v23, v2
	v_and_b32_e32 v23, 0xffff0000, v3
	v_mul_f32_e32 v2, 0xbfb8aa3b, v14
	v_exp_f32_e32 v24, v2
	v_mul_f32_e32 v2, 0xbfb8aa3b, v23
	v_exp_f32_e32 v25, v2
	v_pk_mul_f32 v[2:3], v[20:21], v[6:7]
	v_lshlrev_b32_e32 v6, 16, v15
	v_cvt_pk_bf16_f32 v2, v2, v3
	v_pk_add_f32 v[20:21], v[24:25], 1.0 op_sel_hi:[1,0]
	v_and_b32_e32 v7, 0xffff0000, v15
	v_div_scale_f32 v3, s[6:7], v21, v21, v23
	v_rcp_f32_e32 v24, v3
	v_pk_mul_f32 v[6:7], v[22:23], v[6:7] op_sel_hi:[0,1]
	v_pk_mul_f32 v[6:7], v[8:9], v[6:7]
	v_fma_f32 v8, -v3, v24, 1.0
	v_fmac_f32_e32 v24, v8, v24
	v_div_scale_f32 v8, s[6:7], v20, v20, v14
	v_rcp_f32_e32 v15, v8
	v_rcp_f32_e32 v3, v21
	s_nop 0
	v_mul_f32_e32 v9, v23, v3
	v_fma_f32 v3, -v8, v15, 1.0
	v_fmac_f32_e32 v15, v3, v15
	v_div_scale_f32 v3, vcc, v14, v20, v14
	v_mul_f32_e32 v21, v3, v15
	v_fma_f32 v23, -v8, v21, v3
	v_fmac_f32_e32 v21, v23, v15
	v_rcp_f32_e32 v3, v20
	s_nop 0
	v_mul_f32_e32 v8, v14, v3
	v_lshlrev_b32_e32 v20, 16, v4
	v_and_b32_e32 v4, 0xffff0000, v4
	v_mul_f32_e32 v3, 0xbfb8aa3b, v20
	v_exp_f32_e32 v14, v3
	v_mul_f32_e32 v3, 0xbfb8aa3b, v4
	v_exp_f32_e32 v15, v3
	v_pk_mul_f32 v[6:7], v[8:9], v[6:7]
	v_pk_add_f32 v[8:9], v[14:15], 1.0 op_sel_hi:[1,0]
	s_nop 0
	v_cvt_pk_bf16_f32 v3, v6, v7
	v_lshlrev_b32_e32 v6, 16, v16
	v_and_b32_e32 v7, 0xffff0000, v16
	v_pk_mul_f32 v[6:7], v[22:23], v[6:7] op_sel_hi:[0,1]
	s_waitcnt vmcnt(0)
	v_pk_mul_f32 v[6:7], v[10:11], v[6:7]
	v_div_scale_f32 v14, s[6:7], v8, v8, v20
	v_rcp_f32_e32 v16, v14
	v_rcp_f32_e32 v10, v9
	s_nop 0
	v_mul_f32_e32 v9, v4, v10
	v_and_b32_e32 v15, 0xffff0000, v5
	v_fma_f32 v4, -v14, v16, 1.0
	v_fmac_f32_e32 v16, v4, v16
	v_lshlrev_b32_e32 v14, 16, v5
	v_rcp_f32_e32 v4, v8
	s_nop 0
	v_mul_f32_e32 v8, v20, v4
	v_mul_f32_e32 v4, 0xbfb8aa3b, v14
	v_exp_f32_e32 v10, v4
	v_mul_f32_e32 v4, 0xbfb8aa3b, v15
	v_exp_f32_e32 v11, v4
	v_pk_mul_f32 v[4:5], v[8:9], v[6:7]
	v_lshlrev_b32_e32 v6, 16, v17
	v_cvt_pk_bf16_f32 v4, v4, v5
	v_pk_add_f32 v[8:9], v[10:11], 1.0 op_sel_hi:[1,0]
	v_and_b32_e32 v7, 0xffff0000, v17
	v_pk_mul_f32 v[6:7], v[22:23], v[6:7] op_sel_hi:[0,1]
	v_pk_mul_f32 v[6:7], v[12:13], v[6:7]
	v_div_scale_f32 v11, s[6:7], v8, v8, v14
	v_rcp_f32_e32 v13, v11
	v_rcp_f32_e32 v5, v9
	s_nop 0
	v_mul_f32_e32 v9, v15, v5
	v_fma_f32 v5, -v11, v13, 1.0
	v_fmac_f32_e32 v13, v5, v13
	v_div_scale_f32 v5, vcc, v14, v8, v14
	v_mul_f32_e32 v10, v5, v13
	v_fma_f32 v12, -v11, v10, v5
	v_fmac_f32_e32 v10, v12, v13
	v_rcp_f32_e32 v5, v8
	s_nop 0
	v_mul_f32_e32 v8, v14, v5
	v_pk_mul_f32 v[6:7], v[8:9], v[6:7]
	s_andn2_b64 vcc, exec, s[14:15]
	v_cvt_pk_bf16_f32 v5, v6, v7
	global_store_dwordx4 v[0:1], v[2:5], off sc1
	s_barrier
	s_cbranch_vccz .LBB0_628

.LBB0_1220:
	ds_bpermute_b32 v64, v241, v184
	s_mul_i32 s6, s50, 0x1e00
	s_add_u32 s6, s61, s6
	s_addc_u32 s7, s62, 0
	s_lshl_b32 s10, s49, 1
	s_add_u32 s6, s6, s10
	s_addc_u32 s7, s7, 0
	s_lshl_b32 s8, s50, 12
	s_waitcnt lgkmcnt(0)
	v_add_f32_e32 v72, v184, v64
	s_add_u32 s11, s63, s8
	v_div_scale_f32 v73, s[8:9], v72, v72, 1.0
	v_rcp_f32_e32 v74, v73
	s_addc_u32 s9, s64, 0
	s_add_u32 s8, s11, s10
	s_addc_u32 s9, s9, 0
	v_lshlrev_b32_e32 v144, 1, v150
	v_fma_f32 v64, -v73, v74, 1.0
	v_lshl_add_u64 v[70:71], s[6:7], 0, v[144:145]
	v_lshl_add_u64 v[68:69], s[8:9], 0, v[144:145]
	v_or_b32_e32 v144, s24, v199
	v_fmac_f32_e32 v74, v64, v74
	v_mad_u64_u32 v[64:65], s[6:7], v144, s72, v[70:71]
	s_waitcnt vmcnt(0)
	s_barrier
	global_load_dwordx4 v[64:67], v[64:65], off offset:1024
	v_or_b32_e32 v95, 4, v144
	v_mad_u64_u32 v[130:131], s[6:7], v95, s72, v[70:71]
	global_load_dwordx4 v[100:103], v[130:131], off offset:1024
	v_or_b32_e32 v95, 8, v144
	v_mad_u64_u32 v[132:133], s[6:7], v95, s72, v[70:71]
	global_load_dwordx4 v[104:107], v[132:133], off offset:1024
	v_or_b32_e32 v95, 12, v144
	v_mad_u64_u32 v[134:135], s[6:7], v95, s72, v[70:71]
	global_load_dwordx4 v[108:111], v[134:135], off offset:1024
	v_or_b32_e32 v95, 16, v144
	v_mad_u64_u32 v[136:137], s[6:7], v95, s72, v[70:71]
	global_load_dwordx4 v[112:115], v[136:137], off offset:1024
	v_or_b32_e32 v95, 20, v144
	v_mad_u64_u32 v[138:139], s[6:7], v95, s72, v[70:71]
	global_load_dwordx4 v[116:119], v[138:139], off offset:1024
	v_or_b32_e32 v95, 24, v144
	v_mad_u64_u32 v[140:141], s[6:7], v95, s72, v[70:71]
	global_load_dwordx4 v[120:123], v[140:141], off offset:1024
	v_or_b32_e32 v95, 28, v144
	v_mad_u64_u32 v[142:143], s[6:7], v95, s72, v[70:71]
	global_load_dwordx4 v[124:127], v[142:143], off offset:1024
	v_div_scale_f32 v75, vcc, 1.0, v72, 1.0
	v_mul_f32_e32 v76, v75, v74
	v_fma_f32 v77, -v73, v76, v75
	v_fmac_f32_e32 v76, v77, v74
	v_fma_f32 v73, -v73, v76, v75
	v_div_fmas_f32 v73, v73, v74, v76
	v_div_fixup_f32 v72, v73, v72, 1.0
	v_pk_mul_f32 v[16:17], v[16:17], v[72:73] op_sel_hi:[1,0]
	v_pk_mul_f32 v[18:19], v[18:19], v[72:73] op_sel_hi:[1,0]
	v_cvt_pk_bf16_f32 v16, v16, v17
	v_cvt_pk_bf16_f32 v17, v18, v19
	v_pk_mul_f32 v[18:19], v[20:21], v[72:73] op_sel_hi:[1,0]
	v_pk_mul_f32 v[20:21], v[22:23], v[72:73] op_sel_hi:[1,0]
	v_pk_mul_f32 v[0:1], v[0:1], v[72:73] op_sel_hi:[1,0]
	v_pk_mul_f32 v[2:3], v[2:3], v[72:73] op_sel_hi:[1,0]
	v_mad_u64_u32 v[74:75], s[6:7], v240, s69, v[146:147]
	v_cvt_pk_bf16_f32 v18, v18, v19
	v_cvt_pk_bf16_f32 v19, v20, v21
	v_cvt_pk_bf16_f32 v0, v0, v1
	v_cvt_pk_bf16_f32 v1, v2, v3
	v_pk_mul_f32 v[2:3], v[4:5], v[72:73] op_sel_hi:[1,0]
	v_pk_mul_f32 v[4:5], v[6:7], v[72:73] op_sel_hi:[1,0]
	ds_write2_b64 v74, v[16:17], v[18:19] offset0:16 offset1:18
	v_pk_mul_f32 v[16:17], v[24:25], v[72:73] op_sel_hi:[1,0]
	v_pk_mul_f32 v[18:19], v[26:27], v[72:73] op_sel_hi:[1,0]
	v_cvt_pk_bf16_f32 v2, v2, v3
	v_cvt_pk_bf16_f32 v3, v4, v5
	v_cvt_pk_bf16_f32 v16, v16, v17
	v_cvt_pk_bf16_f32 v17, v18, v19
	v_pk_mul_f32 v[18:19], v[28:29], v[72:73] op_sel_hi:[1,0]
	v_pk_mul_f32 v[20:21], v[30:31], v[72:73] op_sel_hi:[1,0]
	ds_write2_b64 v74, v[0:1], v[2:3] offset0:24 offset1:26
	v_pk_mul_f32 v[0:1], v[8:9], v[72:73] op_sel_hi:[1,0]
	v_pk_mul_f32 v[2:3], v[10:11], v[72:73] op_sel_hi:[1,0]
	v_cvt_pk_bf16_f32 v18, v18, v19
	v_cvt_pk_bf16_f32 v19, v20, v21
	v_cvt_pk_bf16_f32 v0, v0, v1
	v_cvt_pk_bf16_f32 v1, v2, v3
	v_pk_mul_f32 v[2:3], v[12:13], v[72:73] op_sel_hi:[1,0]
	v_pk_mul_f32 v[4:5], v[14:15], v[72:73] op_sel_hi:[1,0]
	v_pk_mul_f32 v[48:49], v[48:49], v[72:73] op_sel_hi:[1,0]
	v_pk_mul_f32 v[50:51], v[50:51], v[72:73] op_sel_hi:[1,0]
	v_pk_mul_f32 v[32:33], v[32:33], v[72:73] op_sel_hi:[1,0]
	v_pk_mul_f32 v[34:35], v[34:35], v[72:73] op_sel_hi:[1,0]
	ds_write2_b64 v74, v[16:17], v[18:19] offset0:20 offset1:22
	v_cvt_pk_bf16_f32 v2, v2, v3
	v_cvt_pk_bf16_f32 v3, v4, v5
	v_cvt_pk_bf16_f32 v48, v48, v49
	v_cvt_pk_bf16_f32 v49, v50, v51
	v_pk_mul_f32 v[50:51], v[52:53], v[72:73] op_sel_hi:[1,0]
	v_pk_mul_f32 v[52:53], v[54:55], v[72:73] op_sel_hi:[1,0]
	v_cvt_pk_bf16_f32 v32, v32, v33
	v_cvt_pk_bf16_f32 v33, v34, v35
	v_pk_mul_f32 v[34:35], v[36:37], v[72:73] op_sel_hi:[1,0]
	v_pk_mul_f32 v[36:37], v[38:39], v[72:73] op_sel_hi:[1,0]
	ds_write2_b64 v74, v[0:1], v[2:3] offset0:28 offset1:30
	v_cvt_pk_bf16_f32 v50, v50, v51
	v_cvt_pk_bf16_f32 v51, v52, v53
	v_cvt_pk_bf16_f32 v34, v34, v35
	v_cvt_pk_bf16_f32 v35, v36, v37
	ds_write2_b64 v74, v[48:49], v[50:51] offset1:2
	v_pk_mul_f32 v[48:49], v[56:57], v[72:73] op_sel_hi:[1,0]
	v_pk_mul_f32 v[50:51], v[58:59], v[72:73] op_sel_hi:[1,0]
	ds_write2_b64 v74, v[32:33], v[34:35] offset0:8 offset1:10
	v_pk_mul_f32 v[32:33], v[40:41], v[72:73] op_sel_hi:[1,0]
	v_pk_mul_f32 v[34:35], v[42:43], v[72:73] op_sel_hi:[1,0]
	v_cvt_pk_bf16_f32 v48, v48, v49
	v_cvt_pk_bf16_f32 v49, v50, v51
	v_pk_mul_f32 v[50:51], v[60:61], v[72:73] op_sel_hi:[1,0]
	v_pk_mul_f32 v[52:53], v[62:63], v[72:73] op_sel_hi:[1,0]
	v_cvt_pk_bf16_f32 v32, v32, v33
	v_cvt_pk_bf16_f32 v33, v34, v35
	v_pk_mul_f32 v[34:35], v[44:45], v[72:73] op_sel_hi:[1,0]
	v_pk_mul_f32 v[36:37], v[46:47], v[72:73] op_sel_hi:[1,0]
	v_cvt_pk_bf16_f32 v50, v50, v51
	v_cvt_pk_bf16_f32 v51, v52, v53
	v_cvt_pk_bf16_f32 v34, v34, v35
	s_waitcnt vmcnt(7)
	v_lshlrev_b32_e32 v16, 16, v64
	v_and_b32_e32 v14, 0xffff0000, v64
	v_mul_f32_e32 v0, 0xbfb8aa3b, v16
	v_mul_f32_e32 v1, 0xbfb8aa3b, v14
	v_exp_f32_e32 v0, v0
	v_exp_f32_e32 v1, v1
	v_cvt_pk_bf16_f32 v35, v36, v37
	ds_write2_b64 v74, v[48:49], v[50:51] offset0:4 offset1:6
	ds_write2_b64 v74, v[32:33], v[34:35] offset0:12 offset1:14
	v_mad_u64_u32 v[12:13], s[6:7], v144, s69, v[148:149]
	v_pk_add_f32 v[8:9], v[0:1], 1.0 op_sel_hi:[1,0]
	ds_read_b128 v[4:7], v12
	ds_read_b128 v[0:3], v12 offset:1088
	s_waitcnt lgkmcnt(1)
	v_lshlrev_b32_e32 v10, 16, v4
	v_and_b32_e32 v11, 0xffff0000, v4
	v_and_b32_e32 v19, 0xffff0000, v65
	v_rcp_f32_e32 v4, v9
	s_nop 0
	v_mul_f32_e32 v9, v14, v4
	v_mul_f32_e32 v15, 0xbfb8aa3b, v19
	v_lshlrev_b32_e32 v13, 16, v65
	v_mul_f32_e32 v14, 0xbfb8aa3b, v13
	v_exp_f32_e32 v14, v14
	v_exp_f32_e32 v15, v15
	v_rcp_f32_e32 v4, v8
	s_nop 0
	v_mul_f32_e32 v8, v16, v4
	v_pk_mul_f32 v[8:9], v[8:9], v[10:11]
	v_pk_add_f32 v[10:11], v[14:15], 1.0 op_sel_hi:[1,0]
	v_cvt_pk_bf16_f32 v4, v8, v9
	v_lshlrev_b32_e32 v8, 16, v5
	v_and_b32_e32 v9, 0xffff0000, v5
	v_lshlrev_b32_e32 v18, 16, v66
	v_rcp_f32_e32 v5, v11
	s_nop 0
	v_mul_f32_e32 v11, v19, v5
	v_and_b32_e32 v19, 0xffff0000, v66
	v_mul_f32_e32 v14, 0xbfb8aa3b, v18
	v_mul_f32_e32 v15, 0xbfb8aa3b, v19
	v_exp_f32_e32 v14, v14
	v_exp_f32_e32 v15, v15
	v_rcp_f32_e32 v5, v10
	s_nop 0
	v_mul_f32_e32 v10, v13, v5
	v_pk_mul_f32 v[8:9], v[10:11], v[8:9]
	v_pk_add_f32 v[10:11], v[14:15], 1.0 op_sel_hi:[1,0]
	v_cvt_pk_bf16_f32 v5, v8, v9
	v_lshlrev_b32_e32 v8, 16, v6
	v_and_b32_e32 v9, 0xffff0000, v6
	v_rcp_f32_e32 v6, v11
	s_nop 0
	v_mul_f32_e32 v11, v19, v6
	v_and_b32_e32 v19, 0xffff0000, v67
	v_lshlrev_b32_e32 v13, 16, v67
	v_mul_f32_e32 v14, 0xbfb8aa3b, v13
	v_mul_f32_e32 v15, 0xbfb8aa3b, v19
	v_exp_f32_e32 v14, v14
	v_exp_f32_e32 v15, v15
	v_rcp_f32_e32 v6, v10
	s_nop 0
	v_mul_f32_e32 v10, v18, v6
	v_pk_mul_f32 v[8:9], v[10:11], v[8:9]
	v_pk_add_f32 v[10:11], v[14:15], 1.0 op_sel_hi:[1,0]
	v_cvt_pk_bf16_f32 v6, v8, v9
	v_lshlrev_b32_e32 v8, 16, v7
	v_and_b32_e32 v9, 0xffff0000, v7
	v_rcp_f32_e32 v7, v11
	s_nop 0
	v_mul_f32_e32 v11, v19, v7
	v_rcp_f32_e32 v7, v10
	s_nop 0
	v_mul_f32_e32 v10, v13, v7
	v_pk_mul_f32 v[8:9], v[10:11], v[8:9]
	s_waitcnt lgkmcnt(0)
	v_lshlrev_b32_e32 v14, 16, v0
	v_cvt_pk_bf16_f32 v7, v8, v9
	v_lshlrev_b64 v[8:9], 12, v[144:145]
	v_lshl_add_u64 v[8:9], v[68:69], 0, v[8:9]
	global_store_dwordx4 v[8:9], v[4:7], off sc1
	v_or_b32_e32 v8, 4, v144
	v_and_b32_e32 v15, 0xffff0000, v0
	v_mad_u64_u32 v[4:5], s[6:7], v8, s72, v[70:71]
	s_waitcnt vmcnt(7)
	v_mov_b32_e32 v4, v100
	v_mov_b32_e32 v5, v101
	v_mov_b32_e32 v6, v102
	v_mov_b32_e32 v7, v103
	v_lshlrev_b32_e32 v13, 16, v4
	v_and_b32_e32 v4, 0xffff0000, v4
	v_mul_f32_e32 v9, 0xbfb8aa3b, v13
	v_exp_f32_e32 v10, v9
	v_mul_f32_e32 v9, 0xbfb8aa3b, v4
	v_exp_f32_e32 v11, v9
	v_mov_b32_e32 v9, v145
	v_pk_add_f32 v[10:11], v[10:11], 1.0 op_sel_hi:[1,0]
	s_nop 0
	s_nop 0
	v_rcp_f32_e32 v0, v11
	s_nop 0
	v_mul_f32_e32 v11, v4, v0
	v_and_b32_e32 v18, 0xffff0000, v5
	v_lshlrev_b32_e32 v16, 16, v5
	v_mul_f32_e32 v4, 0xbfb8aa3b, v16
	v_mul_f32_e32 v5, 0xbfb8aa3b, v18
	v_exp_f32_e32 v4, v4
	v_exp_f32_e32 v5, v5
	v_rcp_f32_e32 v0, v10
	s_nop 0
	v_mul_f32_e32 v10, v13, v0
	v_pk_mul_f32 v[10:11], v[10:11], v[14:15]
	v_pk_add_f32 v[4:5], v[4:5], 1.0 op_sel_hi:[1,0]
	v_cvt_pk_bf16_f32 v0, v10, v11
	v_lshlrev_b32_e32 v10, 16, v1
	v_and_b32_e32 v11, 0xffff0000, v1
	v_rcp_f32_e32 v1, v5
	s_nop 0
	v_mul_f32_e32 v5, v18, v1
	v_lshlrev_b32_e32 v13, 16, v6
	v_and_b32_e32 v6, 0xffff0000, v6
	v_mul_f32_e32 v14, 0xbfb8aa3b, v13
	v_mul_f32_e32 v15, 0xbfb8aa3b, v6
	v_exp_f32_e32 v14, v14
	v_exp_f32_e32 v15, v15
	v_rcp_f32_e32 v1, v4
	s_nop 0
	v_mul_f32_e32 v4, v16, v1
	v_pk_mul_f32 v[4:5], v[4:5], v[10:11]
	v_pk_add_f32 v[10:11], v[14:15], 1.0 op_sel_hi:[1,0]
	v_cvt_pk_bf16_f32 v1, v4, v5
	v_lshlrev_b32_e32 v4, 16, v2
	v_and_b32_e32 v5, 0xffff0000, v2
	v_rcp_f32_e32 v2, v11
	s_nop 0
	v_mul_f32_e32 v11, v6, v2
	v_and_b32_e32 v16, 0xffff0000, v7
	v_lshlrev_b32_e32 v14, 16, v7
	v_mul_f32_e32 v6, 0xbfb8aa3b, v14
	v_mul_f32_e32 v7, 0xbfb8aa3b, v16
	v_exp_f32_e32 v6, v6
	v_exp_f32_e32 v7, v7
	v_rcp_f32_e32 v2, v10
	s_nop 0
	v_mul_f32_e32 v10, v13, v2
	v_pk_mul_f32 v[4:5], v[10:11], v[4:5]
	v_pk_add_f32 v[6:7], v[6:7], 1.0 op_sel_hi:[1,0]
	v_cvt_pk_bf16_f32 v2, v4, v5
	v_lshlrev_b32_e32 v4, 16, v3
	v_and_b32_e32 v5, 0xffff0000, v3
	v_rcp_f32_e32 v3, v7
	s_nop 0
	v_mul_f32_e32 v7, v16, v3
	v_rcp_f32_e32 v3, v6
	s_nop 0
	v_mul_f32_e32 v6, v14, v3
	v_pk_mul_f32 v[4:5], v[6:7], v[4:5]
	v_or_b32_e32 v14, 8, v144
	v_cvt_pk_bf16_f32 v3, v4, v5
	v_lshlrev_b64 v[4:5], 12, v[8:9]
	v_lshl_add_u64 v[4:5], v[68:69], 0, v[4:5]
	global_store_dwordx4 v[4:5], v[0:3], off sc1
	ds_read_b128 v[4:7], v12 offset:2176
	v_mov_b32_e32 v15, v145
	v_mad_u64_u32 v[0:1], s[6:7], v14, s72, v[70:71]
	s_waitcnt vmcnt(7)
	v_mov_b32_e32 v8, v104
	v_mov_b32_e32 v9, v105
	v_mov_b32_e32 v10, v106
	v_mov_b32_e32 v11, v107
	v_lshlrev_b32_e32 v13, 16, v8
	v_and_b32_e32 v8, 0xffff0000, v8
	v_mul_f32_e32 v0, 0xbfb8aa3b, v13
	v_mul_f32_e32 v1, 0xbfb8aa3b, v8
	v_exp_f32_e32 v0, v0
	v_exp_f32_e32 v1, v1
	s_nop 0
	v_pk_add_f32 v[16:17], v[0:1], 1.0 op_sel_hi:[1,0]
	s_nop 0
	ds_read_b128 v[0:3], v12 offset:3264
	s_waitcnt lgkmcnt(1)
	v_lshlrev_b32_e32 v18, 16, v4
	v_and_b32_e32 v19, 0xffff0000, v4
	v_rcp_f32_e32 v4, v17
	s_nop 0
	v_mul_f32_e32 v17, v8, v4
	v_and_b32_e32 v22, 0xffff0000, v9
	v_lshlrev_b32_e32 v20, 16, v9
	v_mul_f32_e32 v8, 0xbfb8aa3b, v20
	v_mul_f32_e32 v9, 0xbfb8aa3b, v22
	v_exp_f32_e32 v8, v8
	v_exp_f32_e32 v9, v9
	v_rcp_f32_e32 v4, v16
	s_nop 0
	v_mul_f32_e32 v16, v13, v4
	v_pk_mul_f32 v[16:17], v[16:17], v[18:19]
	v_pk_add_f32 v[8:9], v[8:9], 1.0 op_sel_hi:[1,0]
	v_cvt_pk_bf16_f32 v4, v16, v17
	v_lshlrev_b32_e32 v16, 16, v5
	v_and_b32_e32 v17, 0xffff0000, v5
	v_rcp_f32_e32 v5, v9
	s_nop 0
	v_mul_f32_e32 v9, v22, v5
	v_lshlrev_b32_e32 v13, 16, v10
	v_and_b32_e32 v10, 0xffff0000, v10
	v_mul_f32_e32 v18, 0xbfb8aa3b, v13
	v_mul_f32_e32 v19, 0xbfb8aa3b, v10
	v_exp_f32_e32 v18, v18
	v_exp_f32_e32 v19, v19
	v_rcp_f32_e32 v5, v8
	s_nop 0
	v_mul_f32_e32 v8, v20, v5
	v_pk_mul_f32 v[8:9], v[8:9], v[16:17]
	v_pk_add_f32 v[16:17], v[18:19], 1.0 op_sel_hi:[1,0]
	v_cvt_pk_bf16_f32 v5, v8, v9
	v_lshlrev_b32_e32 v8, 16, v6
	v_and_b32_e32 v9, 0xffff0000, v6
	v_rcp_f32_e32 v6, v17
	s_nop 0
	v_mul_f32_e32 v17, v10, v6
	v_and_b32_e32 v20, 0xffff0000, v11
	v_lshlrev_b32_e32 v18, 16, v11
	v_mul_f32_e32 v10, 0xbfb8aa3b, v18
	v_mul_f32_e32 v11, 0xbfb8aa3b, v20
	v_exp_f32_e32 v10, v10
	v_exp_f32_e32 v11, v11
	v_rcp_f32_e32 v6, v16
	s_nop 0
	v_mul_f32_e32 v16, v13, v6
	v_pk_mul_f32 v[8:9], v[16:17], v[8:9]
	v_pk_add_f32 v[10:11], v[10:11], 1.0 op_sel_hi:[1,0]
	v_cvt_pk_bf16_f32 v6, v8, v9
	v_lshlrev_b32_e32 v8, 16, v7
	v_and_b32_e32 v9, 0xffff0000, v7
	v_rcp_f32_e32 v7, v11
	s_nop 0
	v_mul_f32_e32 v11, v20, v7
	v_rcp_f32_e32 v7, v10
	s_nop 0
	v_mul_f32_e32 v10, v18, v7
	v_pk_mul_f32 v[8:9], v[10:11], v[8:9]
	s_nop 0
	v_cvt_pk_bf16_f32 v7, v8, v9
	v_lshlrev_b64 v[8:9], 12, v[14:15]
	v_lshl_add_u64 v[8:9], v[68:69], 0, v[8:9]
	global_store_dwordx4 v[8:9], v[4:7], off sc1
	v_or_b32_e32 v8, 12, v144
	s_waitcnt lgkmcnt(0)
	v_lshlrev_b32_e32 v14, 16, v0
	v_mad_u64_u32 v[4:5], s[6:7], v8, s72, v[70:71]
	v_and_b32_e32 v15, 0xffff0000, v0
	s_waitcnt vmcnt(7)
	v_mov_b32_e32 v4, v108
	v_mov_b32_e32 v5, v109
	v_mov_b32_e32 v6, v110
	v_mov_b32_e32 v7, v111
	v_lshlrev_b32_e32 v13, 16, v4
	v_and_b32_e32 v4, 0xffff0000, v4
	v_mul_f32_e32 v9, 0xbfb8aa3b, v13
	v_exp_f32_e32 v10, v9
	v_mul_f32_e32 v9, 0xbfb8aa3b, v4
	v_exp_f32_e32 v11, v9
	v_mov_b32_e32 v9, v145
	v_pk_add_f32 v[10:11], v[10:11], 1.0 op_sel_hi:[1,0]
	s_nop 0
	s_nop 0
	v_rcp_f32_e32 v0, v11
	s_nop 0
	v_mul_f32_e32 v11, v4, v0
	v_and_b32_e32 v18, 0xffff0000, v5
	v_lshlrev_b32_e32 v16, 16, v5
	v_mul_f32_e32 v4, 0xbfb8aa3b, v16
	v_mul_f32_e32 v5, 0xbfb8aa3b, v18
	v_exp_f32_e32 v4, v4
	v_exp_f32_e32 v5, v5
	v_rcp_f32_e32 v0, v10
	s_nop 0
	v_mul_f32_e32 v10, v13, v0
	v_pk_mul_f32 v[10:11], v[10:11], v[14:15]
	v_pk_add_f32 v[4:5], v[4:5], 1.0 op_sel_hi:[1,0]
	v_cvt_pk_bf16_f32 v0, v10, v11
	v_lshlrev_b32_e32 v10, 16, v1
	v_and_b32_e32 v11, 0xffff0000, v1
	v_rcp_f32_e32 v1, v5
	s_nop 0
	v_mul_f32_e32 v5, v18, v1
	v_lshlrev_b32_e32 v13, 16, v6
	v_and_b32_e32 v6, 0xffff0000, v6
	v_mul_f32_e32 v14, 0xbfb8aa3b, v13
	v_mul_f32_e32 v15, 0xbfb8aa3b, v6
	v_exp_f32_e32 v14, v14
	v_exp_f32_e32 v15, v15
	v_rcp_f32_e32 v1, v4
	s_nop 0
	v_mul_f32_e32 v4, v16, v1
	v_pk_mul_f32 v[4:5], v[4:5], v[10:11]
	v_pk_add_f32 v[10:11], v[14:15], 1.0 op_sel_hi:[1,0]
	v_cvt_pk_bf16_f32 v1, v4, v5
	v_lshlrev_b32_e32 v4, 16, v2
	v_and_b32_e32 v5, 0xffff0000, v2
	v_rcp_f32_e32 v2, v11
	s_nop 0
	v_mul_f32_e32 v11, v6, v2
	v_and_b32_e32 v16, 0xffff0000, v7
	v_lshlrev_b32_e32 v14, 16, v7
	v_mul_f32_e32 v6, 0xbfb8aa3b, v14
	v_mul_f32_e32 v7, 0xbfb8aa3b, v16
	v_exp_f32_e32 v6, v6
	v_exp_f32_e32 v7, v7
	v_rcp_f32_e32 v2, v10
	s_nop 0
	v_mul_f32_e32 v10, v13, v2
	v_pk_mul_f32 v[4:5], v[10:11], v[4:5]
	v_pk_add_f32 v[6:7], v[6:7], 1.0 op_sel_hi:[1,0]
	v_cvt_pk_bf16_f32 v2, v4, v5
	v_lshlrev_b32_e32 v4, 16, v3
	v_and_b32_e32 v5, 0xffff0000, v3
	v_rcp_f32_e32 v3, v7
	s_nop 0
	v_mul_f32_e32 v7, v16, v3
	v_rcp_f32_e32 v3, v6
	s_nop 0
	v_mul_f32_e32 v6, v14, v3
	v_pk_mul_f32 v[4:5], v[6:7], v[4:5]
	v_or_b32_e32 v14, 16, v144
	v_cvt_pk_bf16_f32 v3, v4, v5
	v_lshlrev_b64 v[4:5], 12, v[8:9]
	v_lshl_add_u64 v[4:5], v[68:69], 0, v[4:5]
	global_store_dwordx4 v[4:5], v[0:3], off sc1
	ds_read_b128 v[4:7], v12 offset:4352
	v_mov_b32_e32 v15, v145
	v_mad_u64_u32 v[0:1], s[6:7], v14, s72, v[70:71]
	s_waitcnt vmcnt(7)
	v_mov_b32_e32 v8, v112
	v_mov_b32_e32 v9, v113
	v_mov_b32_e32 v10, v114
	v_mov_b32_e32 v11, v115
	v_lshlrev_b32_e32 v13, 16, v8
	v_and_b32_e32 v8, 0xffff0000, v8
	v_mul_f32_e32 v0, 0xbfb8aa3b, v13
	v_mul_f32_e32 v1, 0xbfb8aa3b, v8
	v_exp_f32_e32 v0, v0
	v_exp_f32_e32 v1, v1
	s_nop 0
	v_pk_add_f32 v[16:17], v[0:1], 1.0 op_sel_hi:[1,0]
	s_nop 0
	ds_read_b128 v[0:3], v12 offset:5440
	s_waitcnt lgkmcnt(1)
	v_lshlrev_b32_e32 v18, 16, v4
	v_and_b32_e32 v19, 0xffff0000, v4
	v_div_scale_f32 v20, s[6:7], v16, v16, v13
	v_rcp_f32_e32 v23, v20
	v_rcp_f32_e32 v4, v17
	s_nop 0
	v_mul_f32_e32 v17, v8, v4
	v_and_b32_e32 v22, 0xffff0000, v9
	v_fma_f32 v4, -v20, v23, 1.0
	v_fmac_f32_e32 v23, v4, v23
	v_lshlrev_b32_e32 v20, 16, v9
	v_mul_f32_e32 v8, 0xbfb8aa3b, v20
	v_mul_f32_e32 v9, 0xbfb8aa3b, v22
	v_exp_f32_e32 v8, v8
	v_exp_f32_e32 v9, v9
	v_rcp_f32_e32 v4, v16
	s_nop 0
	v_mul_f32_e32 v16, v13, v4
	v_pk_mul_f32 v[16:17], v[16:17], v[18:19]
	v_pk_add_f32 v[8:9], v[8:9], 1.0 op_sel_hi:[1,0]
	v_cvt_pk_bf16_f32 v4, v16, v17
	v_lshlrev_b32_e32 v16, 16, v5
	v_and_b32_e32 v17, 0xffff0000, v5
	v_rcp_f32_e32 v5, v9
	s_nop 0
	v_mul_f32_e32 v9, v22, v5
	v_lshlrev_b32_e32 v13, 16, v10
	v_and_b32_e32 v10, 0xffff0000, v10
	v_mul_f32_e32 v18, 0xbfb8aa3b, v13
	v_mul_f32_e32 v19, 0xbfb8aa3b, v10
	v_exp_f32_e32 v18, v18
	v_exp_f32_e32 v19, v19
	v_rcp_f32_e32 v5, v8
	s_nop 0
	v_mul_f32_e32 v8, v20, v5
	v_pk_mul_f32 v[8:9], v[8:9], v[16:17]
	v_pk_add_f32 v[16:17], v[18:19], 1.0 op_sel_hi:[1,0]
	v_cvt_pk_bf16_f32 v5, v8, v9
	v_lshlrev_b32_e32 v8, 16, v6
	v_and_b32_e32 v9, 0xffff0000, v6
	v_rcp_f32_e32 v6, v17
	s_nop 0
	v_mul_f32_e32 v17, v10, v6
	v_and_b32_e32 v20, 0xffff0000, v11
	v_lshlrev_b32_e32 v18, 16, v11
	v_mul_f32_e32 v10, 0xbfb8aa3b, v18
	v_mul_f32_e32 v11, 0xbfb8aa3b, v20
	v_exp_f32_e32 v10, v10
	v_exp_f32_e32 v11, v11
	v_rcp_f32_e32 v6, v16
	s_nop 0
	v_mul_f32_e32 v16, v13, v6
	v_pk_mul_f32 v[8:9], v[16:17], v[8:9]
	v_pk_add_f32 v[10:11], v[10:11], 1.0 op_sel_hi:[1,0]
	v_cvt_pk_bf16_f32 v6, v8, v9
	v_lshlrev_b32_e32 v8, 16, v7
	v_and_b32_e32 v9, 0xffff0000, v7
	v_rcp_f32_e32 v7, v11
	s_nop 0
	v_mul_f32_e32 v11, v20, v7
	v_rcp_f32_e32 v7, v10
	s_nop 0
	v_mul_f32_e32 v10, v18, v7
	v_pk_mul_f32 v[8:9], v[10:11], v[8:9]
	s_nop 0
	v_cvt_pk_bf16_f32 v7, v8, v9
	v_lshlrev_b64 v[8:9], 12, v[14:15]
	v_lshl_add_u64 v[8:9], v[68:69], 0, v[8:9]
	global_store_dwordx4 v[8:9], v[4:7], off sc1
	v_or_b32_e32 v8, 20, v144
	s_waitcnt lgkmcnt(0)
	v_lshlrev_b32_e32 v14, 16, v0
	v_mad_u64_u32 v[4:5], s[6:7], v8, s72, v[70:71]
	v_and_b32_e32 v15, 0xffff0000, v0
	s_waitcnt vmcnt(7)
	v_mov_b32_e32 v4, v116
	v_mov_b32_e32 v5, v117
	v_mov_b32_e32 v6, v118
	v_mov_b32_e32 v7, v119
	v_lshlrev_b32_e32 v13, 16, v4
	v_and_b32_e32 v4, 0xffff0000, v4
	v_mul_f32_e32 v9, 0xbfb8aa3b, v13
	v_exp_f32_e32 v10, v9
	v_mul_f32_e32 v9, 0xbfb8aa3b, v4
	v_exp_f32_e32 v11, v9
	v_mov_b32_e32 v9, v145
	v_pk_add_f32 v[10:11], v[10:11], 1.0 op_sel_hi:[1,0]
	s_nop 0
	s_nop 0
	v_rcp_f32_e32 v0, v11
	s_nop 0
	v_mul_f32_e32 v11, v4, v0
	v_and_b32_e32 v18, 0xffff0000, v5
	v_lshlrev_b32_e32 v16, 16, v5
	v_mul_f32_e32 v4, 0xbfb8aa3b, v16
	v_mul_f32_e32 v5, 0xbfb8aa3b, v18
	v_exp_f32_e32 v4, v4
	v_exp_f32_e32 v5, v5
	v_rcp_f32_e32 v0, v10
	s_nop 0
	v_mul_f32_e32 v10, v13, v0
	v_pk_mul_f32 v[10:11], v[10:11], v[14:15]
	v_pk_add_f32 v[4:5], v[4:5], 1.0 op_sel_hi:[1,0]
	v_cvt_pk_bf16_f32 v0, v10, v11
	v_lshlrev_b32_e32 v10, 16, v1
	v_and_b32_e32 v11, 0xffff0000, v1
	v_rcp_f32_e32 v1, v5
	s_nop 0
	v_mul_f32_e32 v5, v18, v1
	v_lshlrev_b32_e32 v13, 16, v6
	v_and_b32_e32 v6, 0xffff0000, v6
	v_mul_f32_e32 v14, 0xbfb8aa3b, v13
	v_mul_f32_e32 v15, 0xbfb8aa3b, v6
	v_exp_f32_e32 v14, v14
	v_exp_f32_e32 v15, v15
	v_rcp_f32_e32 v1, v4
	s_nop 0
	v_mul_f32_e32 v4, v16, v1
	v_pk_mul_f32 v[4:5], v[4:5], v[10:11]
	v_pk_add_f32 v[10:11], v[14:15], 1.0 op_sel_hi:[1,0]
	v_cvt_pk_bf16_f32 v1, v4, v5
	v_lshlrev_b32_e32 v4, 16, v2
	v_and_b32_e32 v5, 0xffff0000, v2
	v_rcp_f32_e32 v2, v11
	s_nop 0
	v_mul_f32_e32 v11, v6, v2
	v_and_b32_e32 v16, 0xffff0000, v7
	v_lshlrev_b32_e32 v14, 16, v7
	v_mul_f32_e32 v6, 0xbfb8aa3b, v14
	v_mul_f32_e32 v7, 0xbfb8aa3b, v16
	v_exp_f32_e32 v6, v6
	v_exp_f32_e32 v7, v7
	v_rcp_f32_e32 v2, v10
	s_nop 0
	v_mul_f32_e32 v10, v13, v2
	v_pk_mul_f32 v[4:5], v[10:11], v[4:5]
	v_pk_add_f32 v[6:7], v[6:7], 1.0 op_sel_hi:[1,0]
	v_cvt_pk_bf16_f32 v2, v4, v5
	v_lshlrev_b32_e32 v4, 16, v3
	v_and_b32_e32 v5, 0xffff0000, v3
	v_rcp_f32_e32 v3, v7
	s_nop 0
	v_mul_f32_e32 v7, v16, v3
	v_rcp_f32_e32 v3, v6
	s_nop 0
	v_mul_f32_e32 v6, v14, v3
	v_pk_mul_f32 v[4:5], v[6:7], v[4:5]
	v_or_b32_e32 v14, 24, v144
	v_cvt_pk_bf16_f32 v3, v4, v5
	v_lshlrev_b64 v[4:5], 12, v[8:9]
	v_lshl_add_u64 v[4:5], v[68:69], 0, v[4:5]
	global_store_dwordx4 v[4:5], v[0:3], off sc1
	ds_read_b128 v[4:7], v12 offset:6528
	v_mov_b32_e32 v15, v145
	v_mad_u64_u32 v[0:1], s[6:7], v14, s72, v[70:71]
	v_or_b32_e32 v144, 28, v144
	s_waitcnt vmcnt(7)
	v_mov_b32_e32 v8, v120
	v_mov_b32_e32 v9, v121
	v_mov_b32_e32 v10, v122
	v_mov_b32_e32 v11, v123
	v_lshlrev_b32_e32 v18, 16, v8
	v_and_b32_e32 v8, 0xffff0000, v8
	v_mul_f32_e32 v0, 0xbfb8aa3b, v18
	v_mul_f32_e32 v1, 0xbfb8aa3b, v8
	v_exp_f32_e32 v0, v0
	v_exp_f32_e32 v1, v1
	s_nop 0
	v_pk_add_f32 v[16:17], v[0:1], 1.0 op_sel_hi:[1,0]
	s_nop 0
	ds_read_b128 v[0:3], v12 offset:7616
	s_waitcnt lgkmcnt(1)
	v_lshlrev_b32_e32 v12, 16, v4
	v_and_b32_e32 v13, 0xffff0000, v4
	v_div_scale_f32 v19, s[6:7], v16, v16, v18
	v_rcp_f32_e32 v22, v19
	v_rcp_f32_e32 v4, v17
	s_nop 0
	v_mul_f32_e32 v17, v8, v4
	v_and_b32_e32 v21, 0xffff0000, v9
	v_fma_f32 v4, -v19, v22, 1.0
	v_fmac_f32_e32 v22, v4, v22
	v_lshlrev_b32_e32 v19, 16, v9
	v_mul_f32_e32 v8, 0xbfb8aa3b, v19
	v_mul_f32_e32 v9, 0xbfb8aa3b, v21
	v_exp_f32_e32 v8, v8
	v_exp_f32_e32 v9, v9
	v_rcp_f32_e32 v4, v16
	s_nop 0
	v_mul_f32_e32 v16, v18, v4
	v_pk_mul_f32 v[12:13], v[16:17], v[12:13]
	v_pk_add_f32 v[8:9], v[8:9], 1.0 op_sel_hi:[1,0]
	v_cvt_pk_bf16_f32 v4, v12, v13
	v_lshlrev_b32_e32 v12, 16, v5
	v_and_b32_e32 v13, 0xffff0000, v5
	v_div_scale_f32 v16, s[6:7], v8, v8, v19
	v_rcp_f32_e32 v20, v16
	v_rcp_f32_e32 v5, v9
	s_nop 0
	v_mul_f32_e32 v9, v21, v5
	v_lshlrev_b32_e32 v21, 16, v10
	v_fma_f32 v5, -v16, v20, 1.0
	v_fmac_f32_e32 v20, v5, v20
	v_and_b32_e32 v10, 0xffff0000, v10
	v_mul_f32_e32 v16, 0xbfb8aa3b, v21
	v_mul_f32_e32 v17, 0xbfb8aa3b, v10
	v_exp_f32_e32 v16, v16
	v_exp_f32_e32 v17, v17
	v_rcp_f32_e32 v5, v8
	s_nop 0
	v_mul_f32_e32 v8, v19, v5
	v_pk_mul_f32 v[8:9], v[8:9], v[12:13]
	v_pk_add_f32 v[12:13], v[16:17], 1.0 op_sel_hi:[1,0]
	v_cvt_pk_bf16_f32 v5, v8, v9
	v_lshlrev_b32_e32 v8, 16, v6
	v_and_b32_e32 v9, 0xffff0000, v6
	v_rcp_f32_e32 v6, v13
	s_nop 0
	v_mul_f32_e32 v13, v10, v6
	v_and_b32_e32 v18, 0xffff0000, v11
	v_lshlrev_b32_e32 v16, 16, v11
	v_mul_f32_e32 v10, 0xbfb8aa3b, v16
	v_mul_f32_e32 v11, 0xbfb8aa3b, v18
	v_exp_f32_e32 v10, v10
	v_exp_f32_e32 v11, v11
	v_rcp_f32_e32 v6, v12
	s_nop 0
	v_mul_f32_e32 v12, v21, v6
	v_pk_mul_f32 v[8:9], v[12:13], v[8:9]
	v_pk_add_f32 v[10:11], v[10:11], 1.0 op_sel_hi:[1,0]
	v_cvt_pk_bf16_f32 v6, v8, v9
	v_lshlrev_b32_e32 v8, 16, v7
	v_and_b32_e32 v9, 0xffff0000, v7
	v_div_scale_f32 v12, s[6:7], v10, v10, v16
	v_rcp_f32_e32 v19, v12
	v_rcp_f32_e32 v7, v11
	s_nop 0
	v_mul_f32_e32 v11, v18, v7
	v_fma_f32 v7, -v12, v19, 1.0
	v_fmac_f32_e32 v19, v7, v19
	v_div_scale_f32 v7, vcc, v16, v10, v16
	v_mul_f32_e32 v13, v7, v19
	v_fma_f32 v17, -v12, v13, v7
	v_rcp_f32_e32 v7, v10
	s_nop 0
	v_mul_f32_e32 v10, v16, v7
	v_pk_mul_f32 v[8:9], v[10:11], v[8:9]
	s_waitcnt lgkmcnt(0)
	v_lshlrev_b32_e32 v10, 16, v0
	v_cvt_pk_bf16_f32 v7, v8, v9
	v_lshlrev_b64 v[8:9], 12, v[14:15]
	v_lshl_add_u64 v[8:9], v[68:69], 0, v[8:9]
	global_store_dwordx4 v[8:9], v[4:7], off sc1
	v_and_b32_e32 v11, 0xffff0000, v0
	s_nop 0
	v_mad_u64_u32 v[4:5], s[6:7], v144, s72, v[70:71]
	s_waitcnt vmcnt(7)
	v_mov_b32_e32 v4, v124
	v_mov_b32_e32 v5, v125
	v_mov_b32_e32 v6, v126
	v_mov_b32_e32 v7, v127
	v_lshlrev_b32_e32 v12, 16, v4
	v_and_b32_e32 v4, 0xffff0000, v4
	v_mul_f32_e32 v8, 0xbfb8aa3b, v12
	v_mul_f32_e32 v9, 0xbfb8aa3b, v4
	v_exp_f32_e32 v8, v8
	v_exp_f32_e32 v9, v9
	s_nop 0
	v_pk_add_f32 v[8:9], v[8:9], 1.0 op_sel_hi:[1,0]
	s_nop 0
	s_nop 0
	v_div_scale_f32 v13, s[6:7], v8, v8, v12
	v_rcp_f32_e32 v16, v13
	v_rcp_f32_e32 v0, v9
	s_nop 0
	v_mul_f32_e32 v9, v4, v0
	v_and_b32_e32 v15, 0xffff0000, v5
	v_fma_f32 v0, -v13, v16, 1.0
	v_fmac_f32_e32 v16, v0, v16
	v_lshlrev_b32_e32 v13, 16, v5
	v_mul_f32_e32 v4, 0xbfb8aa3b, v13
	v_mul_f32_e32 v5, 0xbfb8aa3b, v15
	v_exp_f32_e32 v4, v4
	v_exp_f32_e32 v5, v5
	v_rcp_f32_e32 v0, v8
	s_nop 0
	v_mul_f32_e32 v8, v12, v0
	v_pk_mul_f32 v[8:9], v[8:9], v[10:11]
	v_pk_add_f32 v[4:5], v[4:5], 1.0 op_sel_hi:[1,0]
	v_cvt_pk_bf16_f32 v0, v8, v9
	v_lshlrev_b32_e32 v8, 16, v1
	v_and_b32_e32 v9, 0xffff0000, v1
	v_div_scale_f32 v10, s[6:7], v4, v4, v13
	v_rcp_f32_e32 v14, v10
	v_rcp_f32_e32 v1, v5
	s_nop 0
	v_mul_f32_e32 v5, v15, v1
	v_lshlrev_b32_e32 v15, 16, v6
	v_fma_f32 v1, -v10, v14, 1.0
	v_fmac_f32_e32 v14, v1, v14
	v_and_b32_e32 v6, 0xffff0000, v6
	v_mul_f32_e32 v10, 0xbfb8aa3b, v15
	v_mul_f32_e32 v11, 0xbfb8aa3b, v6
	v_exp_f32_e32 v10, v10
	v_exp_f32_e32 v11, v11
	v_rcp_f32_e32 v1, v4
	s_nop 0
	v_mul_f32_e32 v4, v13, v1
	v_pk_mul_f32 v[4:5], v[4:5], v[8:9]
	v_pk_add_f32 v[8:9], v[10:11], 1.0 op_sel_hi:[1,0]
	v_cvt_pk_bf16_f32 v1, v4, v5
	v_lshlrev_b32_e32 v4, 16, v2
	v_and_b32_e32 v5, 0xffff0000, v2
	v_rcp_f32_e32 v2, v9
	s_nop 0
	v_mul_f32_e32 v9, v6, v2
	v_and_b32_e32 v12, 0xffff0000, v7
	v_lshlrev_b32_e32 v10, 16, v7
	v_mul_f32_e32 v6, 0xbfb8aa3b, v10
	v_mul_f32_e32 v7, 0xbfb8aa3b, v12
	v_exp_f32_e32 v6, v6
	v_exp_f32_e32 v7, v7
	v_rcp_f32_e32 v2, v8
	s_nop 0
	v_mul_f32_e32 v8, v15, v2
	v_pk_mul_f32 v[4:5], v[8:9], v[4:5]
	v_pk_add_f32 v[6:7], v[6:7], 1.0 op_sel_hi:[1,0]
	v_cvt_pk_bf16_f32 v2, v4, v5
	v_lshlrev_b32_e32 v4, 16, v3
	v_and_b32_e32 v5, 0xffff0000, v3
	v_div_scale_f32 v8, s[6:7], v6, v6, v10
	v_rcp_f32_e32 v13, v8
	v_rcp_f32_e32 v3, v7
	s_nop 0
	v_mul_f32_e32 v7, v12, v3
	v_fma_f32 v3, -v8, v13, 1.0
	v_fmac_f32_e32 v13, v3, v13
	v_div_scale_f32 v3, vcc, v10, v6, v10
	v_mul_f32_e32 v9, v3, v13
	v_fma_f32 v11, -v8, v9, v3
	v_fmac_f32_e32 v9, v11, v13
	v_rcp_f32_e32 v3, v6
	s_nop 0
	v_mul_f32_e32 v6, v10, v3
	v_pk_mul_f32 v[4:5], v[6:7], v[4:5]
	s_nop 0
	v_cvt_pk_bf16_f32 v3, v4, v5
	v_lshlrev_b64 v[4:5], 12, v[144:145]
	v_lshl_add_u64 v[4:5], v[68:69], 0, v[4:5]
	global_store_dwordx4 v[4:5], v[0:3], off sc1
	s_barrier

.LBB0_1284:
	v_pk_add_f32 v[64:65], v[80:81], 0 op_sel_hi:[1,0]
	s_lshl_b64 s[6:7], s[38:39], 12
	v_pk_add_f32 v[64:65], v[82:83], v[64:65]
	s_add_u32 s6, s63, s6
	v_pk_add_f32 v[64:65], v[84:85], v[64:65]
	s_addc_u32 s7, s64, s7
	v_pk_add_f32 v[64:65], v[86:87], v[64:65]
	s_add_u32 s6, s6, s87
	v_pk_add_f32 v[64:65], v[88:89], v[64:65]
	s_addc_u32 s7, s7, 0
	v_pk_add_f32 v[64:65], v[90:91], v[64:65]
	v_lshlrev_b32_e32 v144, 1, v150
	v_pk_add_f32 v[64:65], v[92:93], v[64:65]
	s_nop 0
	v_pk_add_f32 v[64:65], v[94:95], v[64:65]
	s_barrier
	v_pk_add_f32 v[64:65], v[96:97], v[64:65]
	s_nop 0
	v_pk_add_f32 v[64:65], v[98:99], v[64:65]
	s_nop 0
	v_pk_add_f32 v[64:65], v[100:101], v[64:65]
	s_nop 0
	v_pk_add_f32 v[64:65], v[102:103], v[64:65]
	s_nop 0
	v_pk_add_f32 v[64:65], v[104:105], v[64:65]
	s_nop 0
	v_pk_add_f32 v[64:65], v[106:107], v[64:65]
	s_nop 0
	v_pk_add_f32 v[64:65], v[108:109], v[64:65]
	s_nop 0
	v_pk_add_f32 v[64:65], v[110:111], v[64:65]
	s_nop 0
	v_add_f32_e32 v64, v64, v65
	v_add_f32_e32 v64, v128, v64
	ds_bpermute_b32 v65, v153, v64
	s_waitcnt lgkmcnt(0)
	v_add_f32_e32 v72, v64, v65
	v_div_scale_f32 v64, s[8:9], v72, v72, 1.0
	v_rcp_f32_e32 v65, v64
	s_add_u32 s8, s85, s87
	s_addc_u32 s9, s86, 0
	v_fma_f32 v66, -v64, v65, 1.0
	v_fmac_f32_e32 v65, v66, v65
	v_div_scale_f32 v66, vcc, 1.0, v72, 1.0
	v_mul_f32_e32 v67, v66, v65
	v_fma_f32 v68, -v64, v67, v66
	v_fmac_f32_e32 v67, v68, v65
	v_fma_f32 v64, -v64, v67, v66
	v_div_fmas_f32 v73, v64, v65, v67
	v_lshl_add_u64 v[64:65], s[8:9], 0, v[144:145]
	v_lshl_add_u64 v[70:71], v[64:65], 0, s[34:35]
	v_lshl_add_u64 v[68:69], s[6:7], 0, v[144:145]
	v_or_b32_e32 v144, s82, v199
	v_mad_u64_u32 v[64:65], s[6:7], v144, s72, v[70:71]
	global_load_dwordx4 v[64:67], v[64:65], off
	v_div_fixup_f32 v72, v73, v72, 1.0
	v_pk_mul_f32 v[0:1], v[0:1], v[72:73] op_sel_hi:[1,0]
	v_pk_mul_f32 v[2:3], v[2:3], v[72:73] op_sel_hi:[1,0]
	v_cvt_pk_bf16_f32 v0, v0, v1
	v_cvt_pk_bf16_f32 v1, v2, v3
	v_pk_mul_f32 v[2:3], v[4:5], v[72:73] op_sel_hi:[1,0]
	v_pk_mul_f32 v[4:5], v[6:7], v[72:73] op_sel_hi:[1,0]
	v_mad_u64_u32 v[74:75], s[6:7], v180, s69, v[146:147]
	v_pk_mul_f32 v[16:17], v[16:17], v[72:73] op_sel_hi:[1,0]
	v_pk_mul_f32 v[18:19], v[18:19], v[72:73] op_sel_hi:[1,0]
	v_cvt_pk_bf16_f32 v2, v2, v3
	v_cvt_pk_bf16_f32 v3, v4, v5
	v_cvt_pk_bf16_f32 v16, v16, v17
	v_cvt_pk_bf16_f32 v17, v18, v19
	v_pk_mul_f32 v[18:19], v[20:21], v[72:73] op_sel_hi:[1,0]
	v_pk_mul_f32 v[20:21], v[22:23], v[72:73] op_sel_hi:[1,0]
	ds_write2_b64 v74, v[0:1], v[2:3] offset0:24 offset1:26
	v_pk_mul_f32 v[0:1], v[8:9], v[72:73] op_sel_hi:[1,0]
	v_pk_mul_f32 v[2:3], v[10:11], v[72:73] op_sel_hi:[1,0]
	v_cvt_pk_bf16_f32 v18, v18, v19
	v_cvt_pk_bf16_f32 v19, v20, v21
	v_cvt_pk_bf16_f32 v0, v0, v1
	v_cvt_pk_bf16_f32 v1, v2, v3
	v_pk_mul_f32 v[2:3], v[12:13], v[72:73] op_sel_hi:[1,0]
	v_pk_mul_f32 v[4:5], v[14:15], v[72:73] op_sel_hi:[1,0]
	ds_write2_b64 v74, v[16:17], v[18:19] offset0:16 offset1:18
	v_pk_mul_f32 v[16:17], v[24:25], v[72:73] op_sel_hi:[1,0]
	v_pk_mul_f32 v[18:19], v[26:27], v[72:73] op_sel_hi:[1,0]
	v_cvt_pk_bf16_f32 v2, v2, v3
	v_cvt_pk_bf16_f32 v3, v4, v5
	v_or_b32_e32 v14, 4, v144
	v_cvt_pk_bf16_f32 v16, v16, v17
	v_cvt_pk_bf16_f32 v17, v18, v19
	v_pk_mul_f32 v[18:19], v[28:29], v[72:73] op_sel_hi:[1,0]
	v_pk_mul_f32 v[20:21], v[30:31], v[72:73] op_sel_hi:[1,0]
	ds_write2_b64 v74, v[0:1], v[2:3] offset0:28 offset1:30
	v_mad_u64_u32 v[0:1], s[6:7], v14, s72, v[70:71]
	v_pk_mul_f32 v[48:49], v[48:49], v[72:73] op_sel_hi:[1,0]
	v_pk_mul_f32 v[50:51], v[50:51], v[72:73] op_sel_hi:[1,0]
	v_pk_mul_f32 v[32:33], v[32:33], v[72:73] op_sel_hi:[1,0]
	v_pk_mul_f32 v[34:35], v[34:35], v[72:73] op_sel_hi:[1,0]
	v_cvt_pk_bf16_f32 v18, v18, v19
	v_cvt_pk_bf16_f32 v19, v20, v21
	global_load_dwordx4 v[4:7], v[0:1], off
	v_cvt_pk_bf16_f32 v48, v48, v49
	v_cvt_pk_bf16_f32 v49, v50, v51
	v_pk_mul_f32 v[50:51], v[52:53], v[72:73] op_sel_hi:[1,0]
	v_pk_mul_f32 v[52:53], v[54:55], v[72:73] op_sel_hi:[1,0]
	v_cvt_pk_bf16_f32 v32, v32, v33
	v_cvt_pk_bf16_f32 v33, v34, v35
	v_pk_mul_f32 v[34:35], v[36:37], v[72:73] op_sel_hi:[1,0]
	v_pk_mul_f32 v[36:37], v[38:39], v[72:73] op_sel_hi:[1,0]
	v_cvt_pk_bf16_f32 v50, v50, v51
	v_cvt_pk_bf16_f32 v51, v52, v53
	v_cvt_pk_bf16_f32 v34, v34, v35
	v_cvt_pk_bf16_f32 v35, v36, v37
	ds_write2_b64 v74, v[48:49], v[50:51] offset1:2
	v_pk_mul_f32 v[48:49], v[56:57], v[72:73] op_sel_hi:[1,0]
	v_pk_mul_f32 v[50:51], v[58:59], v[72:73] op_sel_hi:[1,0]
	ds_write2_b64 v74, v[32:33], v[34:35] offset0:8 offset1:10
	v_pk_mul_f32 v[32:33], v[40:41], v[72:73] op_sel_hi:[1,0]
	v_pk_mul_f32 v[34:35], v[42:43], v[72:73] op_sel_hi:[1,0]
	v_cvt_pk_bf16_f32 v48, v48, v49
	v_cvt_pk_bf16_f32 v49, v50, v51
	v_pk_mul_f32 v[50:51], v[60:61], v[72:73] op_sel_hi:[1,0]
	v_pk_mul_f32 v[52:53], v[62:63], v[72:73] op_sel_hi:[1,0]
	v_cvt_pk_bf16_f32 v32, v32, v33
	v_cvt_pk_bf16_f32 v33, v34, v35
	v_pk_mul_f32 v[34:35], v[44:45], v[72:73] op_sel_hi:[1,0]
	v_pk_mul_f32 v[36:37], v[46:47], v[72:73] op_sel_hi:[1,0]
	v_cvt_pk_bf16_f32 v50, v50, v51
	v_cvt_pk_bf16_f32 v51, v52, v53
	v_cvt_pk_bf16_f32 v34, v34, v35
	v_cvt_pk_bf16_f32 v35, v36, v37
	ds_write2_b64 v74, v[48:49], v[50:51] offset0:4 offset1:6
	ds_write2_b64 v74, v[32:33], v[34:35] offset0:12 offset1:14
	ds_write2_b64 v74, v[16:17], v[18:19] offset0:20 offset1:22
	s_waitcnt vmcnt(1)
	v_lshlrev_b32_e32 v15, 16, v64
	v_and_b32_e32 v20, 0xffff0000, v64
	v_mul_f32_e32 v0, 0xbfb8aa3b, v15
	v_mul_f32_e32 v1, 0xbfb8aa3b, v20
	v_exp_f32_e32 v0, v0
	v_exp_f32_e32 v1, v1
	v_mad_u64_u32 v[12:13], s[6:7], v144, s69, v[148:149]
	ds_read_b128 v[8:11], v12
	v_pk_add_f32 v[16:17], v[0:1], 1.0 op_sel_hi:[1,0]
	ds_read_b128 v[0:3], v12 offset:1088
	s_waitcnt lgkmcnt(1)
	v_lshlrev_b32_e32 v18, 16, v8
	v_and_b32_e32 v19, 0xffff0000, v8
	v_and_b32_e32 v24, 0xffff0000, v65
	v_rcp_f32_e32 v8, v17
	s_nop 0
	v_mul_f32_e32 v17, v20, v8
	v_mul_f32_e32 v21, 0xbfb8aa3b, v24
	v_lshlrev_b32_e32 v13, 16, v65
	v_mul_f32_e32 v20, 0xbfb8aa3b, v13
	v_exp_f32_e32 v20, v20
	v_exp_f32_e32 v21, v21
	v_rcp_f32_e32 v8, v16
	s_nop 0
	v_mul_f32_e32 v16, v15, v8
	v_pk_mul_f32 v[16:17], v[16:17], v[18:19]
	v_pk_add_f32 v[18:19], v[20:21], 1.0 op_sel_hi:[1,0]
	v_cvt_pk_bf16_f32 v8, v16, v17
	v_lshlrev_b32_e32 v16, 16, v9
	v_and_b32_e32 v17, 0xffff0000, v9
	v_rcp_f32_e32 v9, v19
	s_nop 0
	v_mul_f32_e32 v19, v24, v9
	v_and_b32_e32 v24, 0xffff0000, v66
	v_lshlrev_b32_e32 v15, 16, v66
	v_mul_f32_e32 v20, 0xbfb8aa3b, v15
	v_mul_f32_e32 v21, 0xbfb8aa3b, v24
	v_exp_f32_e32 v20, v20
	v_exp_f32_e32 v21, v21
	v_rcp_f32_e32 v9, v18
	s_nop 0
	v_mul_f32_e32 v18, v13, v9
	v_pk_mul_f32 v[16:17], v[18:19], v[16:17]
	v_pk_add_f32 v[18:19], v[20:21], 1.0 op_sel_hi:[1,0]
	v_cvt_pk_bf16_f32 v9, v16, v17
	v_lshlrev_b32_e32 v16, 16, v10
	v_and_b32_e32 v17, 0xffff0000, v10
	v_rcp_f32_e32 v10, v19
	s_nop 0
	v_mul_f32_e32 v19, v24, v10
	v_and_b32_e32 v24, 0xffff0000, v67
	v_lshlrev_b32_e32 v13, 16, v67
	v_mul_f32_e32 v20, 0xbfb8aa3b, v13
	v_mul_f32_e32 v21, 0xbfb8aa3b, v24
	v_exp_f32_e32 v20, v20
	v_exp_f32_e32 v21, v21
	v_rcp_f32_e32 v10, v18
	s_nop 0
	v_mul_f32_e32 v18, v15, v10
	v_pk_mul_f32 v[16:17], v[18:19], v[16:17]
	v_pk_add_f32 v[18:19], v[20:21], 1.0 op_sel_hi:[1,0]
	v_cvt_pk_bf16_f32 v10, v16, v17
	v_lshlrev_b32_e32 v16, 16, v11
	v_and_b32_e32 v17, 0xffff0000, v11
	v_rcp_f32_e32 v11, v19
	s_nop 0
	v_mul_f32_e32 v19, v24, v11
	v_rcp_f32_e32 v11, v18
	s_nop 0
	v_mul_f32_e32 v18, v13, v11
	s_waitcnt vmcnt(0)
	v_lshlrev_b32_e32 v13, 16, v4
	v_pk_mul_f32 v[16:17], v[18:19], v[16:17]
	v_and_b32_e32 v4, 0xffff0000, v4
	v_mul_f32_e32 v15, 0xbfb8aa3b, v13
	v_cvt_pk_bf16_f32 v11, v16, v17
	v_exp_f32_e32 v16, v15
	v_mul_f32_e32 v15, 0xbfb8aa3b, v4
	v_exp_f32_e32 v17, v15
	v_lshlrev_b64 v[18:19], 12, v[144:145]
	v_lshl_add_u64 v[18:19], v[68:69], 0, v[18:19]
	global_store_dwordx4 v[18:19], v[8:11], off offset:3072 sc1
	v_mov_b32_e32 v15, v145
	s_nop 0
	v_pk_add_f32 v[8:9], v[16:17], 1.0 op_sel_hi:[1,0]
	s_waitcnt lgkmcnt(0)
	v_lshlrev_b32_e32 v10, 16, v0
	v_and_b32_e32 v11, 0xffff0000, v0
	v_rcp_f32_e32 v0, v9
	s_nop 0
	v_mul_f32_e32 v9, v4, v0
	v_and_b32_e32 v18, 0xffff0000, v5
	v_lshlrev_b32_e32 v16, 16, v5
	v_mul_f32_e32 v4, 0xbfb8aa3b, v16
	v_mul_f32_e32 v5, 0xbfb8aa3b, v18
	v_exp_f32_e32 v4, v4
	v_exp_f32_e32 v5, v5
	v_rcp_f32_e32 v0, v8
	s_nop 0
	v_mul_f32_e32 v8, v13, v0
	v_pk_mul_f32 v[8:9], v[8:9], v[10:11]
	v_pk_add_f32 v[4:5], v[4:5], 1.0 op_sel_hi:[1,0]
	v_cvt_pk_bf16_f32 v0, v8, v9
	v_lshlrev_b32_e32 v8, 16, v1
	v_and_b32_e32 v9, 0xffff0000, v1
	v_rcp_f32_e32 v1, v5
	s_nop 0
	v_mul_f32_e32 v5, v18, v1
	v_rcp_f32_e32 v1, v4
	s_nop 0
	v_mul_f32_e32 v4, v16, v1
	v_or_b32_e32 v16, 8, v144
	v_pk_mul_f32 v[4:5], v[4:5], v[8:9]
	v_mad_u64_u32 v[8:9], s[6:7], v16, s72, v[70:71]
	global_load_dwordx4 v[8:11], v[8:9], off
	v_lshlrev_b32_e32 v13, 16, v6
	v_and_b32_e32 v6, 0xffff0000, v6
	v_mul_f32_e32 v1, 0xbfb8aa3b, v13
	v_exp_f32_e32 v18, v1
	v_mul_f32_e32 v1, 0xbfb8aa3b, v6
	v_exp_f32_e32 v19, v1
	v_cvt_pk_bf16_f32 v1, v4, v5
	v_lshlrev_b32_e32 v4, 16, v2
	v_and_b32_e32 v5, 0xffff0000, v2
	v_pk_add_f32 v[18:19], v[18:19], 1.0 op_sel_hi:[1,0]
	s_nop 0
	s_nop 0
	v_rcp_f32_e32 v2, v19
	s_nop 0
	v_mul_f32_e32 v19, v6, v2
	v_and_b32_e32 v21, 0xffff0000, v7
	v_lshlrev_b32_e32 v17, 16, v7
	v_mul_f32_e32 v6, 0xbfb8aa3b, v17
	v_mul_f32_e32 v7, 0xbfb8aa3b, v21
	v_exp_f32_e32 v6, v6
	v_exp_f32_e32 v7, v7
	v_rcp_f32_e32 v2, v18
	s_nop 0
	v_mul_f32_e32 v18, v13, v2
	v_pk_mul_f32 v[4:5], v[18:19], v[4:5]
	v_pk_add_f32 v[6:7], v[6:7], 1.0 op_sel_hi:[1,0]
	v_cvt_pk_bf16_f32 v2, v4, v5
	v_lshlrev_b32_e32 v4, 16, v3
	v_and_b32_e32 v5, 0xffff0000, v3
	v_rcp_f32_e32 v3, v7
	s_nop 0
	v_mul_f32_e32 v7, v21, v3
	v_rcp_f32_e32 v3, v6
	s_nop 0
	v_mul_f32_e32 v6, v17, v3
	v_pk_mul_f32 v[4:5], v[6:7], v[4:5]
	v_mov_b32_e32 v17, v145
	v_cvt_pk_bf16_f32 v3, v4, v5
	v_lshlrev_b64 v[4:5], 12, v[14:15]
	v_or_b32_e32 v14, 12, v144
	v_lshl_add_u64 v[18:19], v[68:69], 0, v[4:5]
	v_mad_u64_u32 v[4:5], s[6:7], v14, s72, v[70:71]
	global_load_dwordx4 v[4:7], v[4:5], off
	s_waitcnt vmcnt(1)
	v_lshlrev_b32_e32 v13, 16, v8
	v_and_b32_e32 v8, 0xffff0000, v8
	v_mul_f32_e32 v15, 0xbfb8aa3b, v13
	v_exp_f32_e32 v22, v15
	v_mul_f32_e32 v15, 0xbfb8aa3b, v8
	v_exp_f32_e32 v23, v15
	global_store_dwordx4 v[18:19], v[0:3], off offset:3072 sc1
	ds_read_b128 v[18:21], v12 offset:2176
	ds_read_b128 v[0:3], v12 offset:3264
	v_pk_add_f32 v[22:23], v[22:23], 1.0 op_sel_hi:[1,0]
	v_lshlrev_b32_e32 v29, 16, v9
	s_waitcnt lgkmcnt(1)
	v_lshlrev_b32_e32 v24, 16, v18
	v_and_b32_e32 v25, 0xffff0000, v18
	v_lshlrev_b64 v[16:17], 12, v[16:17]
	v_rcp_f32_e32 v15, v23
	s_nop 0
	v_mul_f32_e32 v23, v8, v15
	v_lshl_add_u64 v[16:17], v[68:69], 0, v[16:17]
	v_and_b32_e32 v26, 0xffff0000, v9
	v_mul_f32_e32 v8, 0xbfb8aa3b, v29
	v_mul_f32_e32 v9, 0xbfb8aa3b, v26
	v_exp_f32_e32 v8, v8
	v_exp_f32_e32 v9, v9
	v_rcp_f32_e32 v15, v22
	s_nop 0
	v_mul_f32_e32 v22, v13, v15
	v_pk_mul_f32 v[22:23], v[22:23], v[24:25]
	v_pk_add_f32 v[24:25], v[8:9], 1.0 op_sel_hi:[1,0]
	v_cvt_pk_bf16_f32 v8, v22, v23
	v_lshlrev_b32_e32 v18, 16, v19
	v_and_b32_e32 v19, 0xffff0000, v19
	v_rcp_f32_e32 v9, v25
	s_nop 0
	v_mul_f32_e32 v23, v26, v9
	v_lshlrev_b32_e32 v15, 16, v10
	v_and_b32_e32 v10, 0xffff0000, v10
	v_mul_f32_e32 v22, 0xbfb8aa3b, v15
	v_exp_f32_e32 v26, v22
	v_mul_f32_e32 v22, 0xbfb8aa3b, v10
	v_exp_f32_e32 v27, v22
	v_rcp_f32_e32 v9, v24
	s_nop 0
	v_mul_f32_e32 v22, v29, v9
	v_pk_mul_f32 v[18:19], v[22:23], v[18:19]
	v_pk_add_f32 v[22:23], v[26:27], 1.0 op_sel_hi:[1,0]
	v_cvt_pk_bf16_f32 v9, v18, v19
	v_lshlrev_b32_e32 v18, 16, v20
	v_and_b32_e32 v19, 0xffff0000, v20
	v_rcp_f32_e32 v13, v23
	s_nop 0
	v_mul_f32_e32 v23, v10, v13
	v_and_b32_e32 v25, 0xffff0000, v11
	v_lshlrev_b32_e32 v24, 16, v11
	v_mul_f32_e32 v10, 0xbfb8aa3b, v24
	v_mul_f32_e32 v11, 0xbfb8aa3b, v25
	v_exp_f32_e32 v10, v10
	v_exp_f32_e32 v11, v11
	v_rcp_f32_e32 v13, v22
	s_nop 0
	v_mul_f32_e32 v22, v15, v13
	v_pk_mul_f32 v[18:19], v[22:23], v[18:19]
	v_pk_add_f32 v[22:23], v[10:11], 1.0 op_sel_hi:[1,0]
	v_cvt_pk_bf16_f32 v10, v18, v19
	v_lshlrev_b32_e32 v18, 16, v21
	v_and_b32_e32 v19, 0xffff0000, v21
	v_rcp_f32_e32 v11, v23
	s_nop 0
	v_mul_f32_e32 v21, v25, v11
	v_rcp_f32_e32 v11, v22
	s_nop 0
	v_mul_f32_e32 v20, v24, v11
	s_waitcnt vmcnt(1)
	v_lshlrev_b32_e32 v13, 16, v4
	v_pk_mul_f32 v[18:19], v[20:21], v[18:19]
	v_and_b32_e32 v4, 0xffff0000, v4
	v_mul_f32_e32 v15, 0xbfb8aa3b, v13
	v_cvt_pk_bf16_f32 v11, v18, v19
	v_exp_f32_e32 v18, v15
	v_mul_f32_e32 v15, 0xbfb8aa3b, v4
	v_exp_f32_e32 v19, v15
	global_store_dwordx4 v[16:17], v[8:11], off offset:3072 sc1
	v_mov_b32_e32 v15, v145
	s_nop 0
	v_pk_add_f32 v[8:9], v[18:19], 1.0 op_sel_hi:[1,0]
	s_waitcnt lgkmcnt(0)
	v_lshlrev_b32_e32 v10, 16, v0
	v_and_b32_e32 v11, 0xffff0000, v0
	v_rcp_f32_e32 v0, v9
	s_nop 0
	v_mul_f32_e32 v9, v4, v0
	v_and_b32_e32 v18, 0xffff0000, v5
	v_lshlrev_b32_e32 v16, 16, v5
	v_mul_f32_e32 v4, 0xbfb8aa3b, v16
	v_mul_f32_e32 v5, 0xbfb8aa3b, v18
	v_exp_f32_e32 v4, v4
	v_exp_f32_e32 v5, v5
	v_rcp_f32_e32 v0, v8
	s_nop 0
	v_mul_f32_e32 v8, v13, v0
	v_pk_mul_f32 v[8:9], v[8:9], v[10:11]
	v_pk_add_f32 v[4:5], v[4:5], 1.0 op_sel_hi:[1,0]
	v_cvt_pk_bf16_f32 v0, v8, v9
	v_lshlrev_b32_e32 v8, 16, v1
	v_and_b32_e32 v9, 0xffff0000, v1
	v_rcp_f32_e32 v1, v5
	s_nop 0
	v_mul_f32_e32 v5, v18, v1
	v_rcp_f32_e32 v1, v4
	s_nop 0
	v_mul_f32_e32 v4, v16, v1
	v_or_b32_e32 v16, 16, v144
	v_pk_mul_f32 v[4:5], v[4:5], v[8:9]
	v_mad_u64_u32 v[8:9], s[6:7], v16, s72, v[70:71]
	global_load_dwordx4 v[8:11], v[8:9], off
	v_lshlrev_b32_e32 v13, 16, v6
	v_and_b32_e32 v6, 0xffff0000, v6
	v_mul_f32_e32 v1, 0xbfb8aa3b, v13
	v_exp_f32_e32 v18, v1
	v_mul_f32_e32 v1, 0xbfb8aa3b, v6
	v_exp_f32_e32 v19, v1
	v_cvt_pk_bf16_f32 v1, v4, v5
	v_lshlrev_b32_e32 v4, 16, v2
	v_and_b32_e32 v5, 0xffff0000, v2
	v_pk_add_f32 v[18:19], v[18:19], 1.0 op_sel_hi:[1,0]
	s_nop 0
	s_nop 0
	v_rcp_f32_e32 v2, v19
	s_nop 0
	v_mul_f32_e32 v19, v6, v2
	v_and_b32_e32 v21, 0xffff0000, v7
	v_lshlrev_b32_e32 v17, 16, v7
	v_mul_f32_e32 v6, 0xbfb8aa3b, v17
	v_mul_f32_e32 v7, 0xbfb8aa3b, v21
	v_exp_f32_e32 v6, v6
	v_exp_f32_e32 v7, v7
	v_rcp_f32_e32 v2, v18
	s_nop 0
	v_mul_f32_e32 v18, v13, v2
	v_pk_mul_f32 v[4:5], v[18:19], v[4:5]
	v_pk_add_f32 v[6:7], v[6:7], 1.0 op_sel_hi:[1,0]
	v_cvt_pk_bf16_f32 v2, v4, v5
	v_lshlrev_b32_e32 v4, 16, v3
	v_and_b32_e32 v5, 0xffff0000, v3
	v_rcp_f32_e32 v3, v7
	s_nop 0
	v_mul_f32_e32 v7, v21, v3
	v_rcp_f32_e32 v3, v6
	s_nop 0
	v_mul_f32_e32 v6, v17, v3
	v_pk_mul_f32 v[4:5], v[6:7], v[4:5]
	v_mov_b32_e32 v17, v145
	v_cvt_pk_bf16_f32 v3, v4, v5
	v_lshlrev_b64 v[4:5], 12, v[14:15]
	v_or_b32_e32 v14, 20, v144
	v_lshl_add_u64 v[18:19], v[68:69], 0, v[4:5]
	v_mad_u64_u32 v[4:5], s[6:7], v14, s72, v[70:71]
	global_load_dwordx4 v[4:7], v[4:5], off
	s_waitcnt vmcnt(1)
	v_lshlrev_b32_e32 v13, 16, v8
	v_and_b32_e32 v8, 0xffff0000, v8
	v_mul_f32_e32 v15, 0xbfb8aa3b, v13
	v_exp_f32_e32 v22, v15
	v_mul_f32_e32 v15, 0xbfb8aa3b, v8
	v_exp_f32_e32 v23, v15
	global_store_dwordx4 v[18:19], v[0:3], off offset:3072 sc1
	ds_read_b128 v[18:21], v12 offset:4352
	ds_read_b128 v[0:3], v12 offset:5440
	v_pk_add_f32 v[22:23], v[22:23], 1.0 op_sel_hi:[1,0]
	v_lshlrev_b32_e32 v29, 16, v9
	s_waitcnt lgkmcnt(1)
	v_lshlrev_b32_e32 v24, 16, v18
	v_and_b32_e32 v25, 0xffff0000, v18
	v_lshlrev_b64 v[16:17], 12, v[16:17]
	v_rcp_f32_e32 v15, v23
	s_nop 0
	v_mul_f32_e32 v23, v8, v15
	v_lshl_add_u64 v[16:17], v[68:69], 0, v[16:17]
	v_and_b32_e32 v26, 0xffff0000, v9
	v_mul_f32_e32 v8, 0xbfb8aa3b, v29
	v_mul_f32_e32 v9, 0xbfb8aa3b, v26
	v_exp_f32_e32 v8, v8
	v_exp_f32_e32 v9, v9
	v_rcp_f32_e32 v15, v22
	s_nop 0
	v_mul_f32_e32 v22, v13, v15
	v_pk_mul_f32 v[22:23], v[22:23], v[24:25]
	v_pk_add_f32 v[24:25], v[8:9], 1.0 op_sel_hi:[1,0]
	v_cvt_pk_bf16_f32 v8, v22, v23
	v_lshlrev_b32_e32 v18, 16, v19
	v_and_b32_e32 v19, 0xffff0000, v19
	v_div_scale_f32 v15, s[6:7], v24, v24, v29
	v_rcp_f32_e32 v28, v15
	v_rcp_f32_e32 v9, v25
	s_nop 0
	v_mul_f32_e32 v23, v26, v9
	v_fma_f32 v9, -v15, v28, 1.0
	v_fmac_f32_e32 v28, v9, v28
	v_lshlrev_b32_e32 v15, 16, v10
	v_and_b32_e32 v10, 0xffff0000, v10
	v_mul_f32_e32 v22, 0xbfb8aa3b, v15
	v_exp_f32_e32 v26, v22
	v_mul_f32_e32 v22, 0xbfb8aa3b, v10
	v_exp_f32_e32 v27, v22
	v_rcp_f32_e32 v9, v24
	s_nop 0
	v_mul_f32_e32 v22, v29, v9
	v_pk_mul_f32 v[18:19], v[22:23], v[18:19]
	v_pk_add_f32 v[22:23], v[26:27], 1.0 op_sel_hi:[1,0]
	v_cvt_pk_bf16_f32 v9, v18, v19
	v_lshlrev_b32_e32 v18, 16, v20
	v_and_b32_e32 v19, 0xffff0000, v20
	v_rcp_f32_e32 v13, v23
	s_nop 0
	v_mul_f32_e32 v23, v10, v13
	v_and_b32_e32 v25, 0xffff0000, v11
	v_lshlrev_b32_e32 v24, 16, v11
	v_mul_f32_e32 v10, 0xbfb8aa3b, v24
	v_mul_f32_e32 v11, 0xbfb8aa3b, v25
	v_exp_f32_e32 v10, v10
	v_exp_f32_e32 v11, v11
	v_rcp_f32_e32 v13, v22
	s_nop 0
	v_mul_f32_e32 v22, v15, v13
	v_pk_mul_f32 v[18:19], v[22:23], v[18:19]
	v_pk_add_f32 v[22:23], v[10:11], 1.0 op_sel_hi:[1,0]
	v_cvt_pk_bf16_f32 v10, v18, v19
	v_lshlrev_b32_e32 v18, 16, v21
	v_and_b32_e32 v19, 0xffff0000, v21
	v_rcp_f32_e32 v11, v23
	s_nop 0
	v_mul_f32_e32 v21, v25, v11
	v_rcp_f32_e32 v11, v22
	s_nop 0
	v_mul_f32_e32 v20, v24, v11
	s_waitcnt vmcnt(1)
	v_lshlrev_b32_e32 v13, 16, v4
	v_pk_mul_f32 v[18:19], v[20:21], v[18:19]
	v_and_b32_e32 v4, 0xffff0000, v4
	v_mul_f32_e32 v15, 0xbfb8aa3b, v13
	v_cvt_pk_bf16_f32 v11, v18, v19
	v_exp_f32_e32 v18, v15
	v_mul_f32_e32 v15, 0xbfb8aa3b, v4
	v_exp_f32_e32 v19, v15
	global_store_dwordx4 v[16:17], v[8:11], off offset:3072 sc1
	v_mov_b32_e32 v15, v145
	s_nop 0
	v_pk_add_f32 v[8:9], v[18:19], 1.0 op_sel_hi:[1,0]
	s_waitcnt lgkmcnt(0)
	v_lshlrev_b32_e32 v10, 16, v0
	v_and_b32_e32 v11, 0xffff0000, v0
	v_rcp_f32_e32 v0, v9
	s_nop 0
	v_mul_f32_e32 v9, v4, v0
	v_and_b32_e32 v18, 0xffff0000, v5
	v_lshlrev_b32_e32 v16, 16, v5
	v_mul_f32_e32 v4, 0xbfb8aa3b, v16
	v_mul_f32_e32 v5, 0xbfb8aa3b, v18
	v_exp_f32_e32 v4, v4
	v_exp_f32_e32 v5, v5
	v_rcp_f32_e32 v0, v8
	s_nop 0
	v_mul_f32_e32 v8, v13, v0
	v_pk_mul_f32 v[8:9], v[8:9], v[10:11]
	v_pk_add_f32 v[4:5], v[4:5], 1.0 op_sel_hi:[1,0]
	v_cvt_pk_bf16_f32 v0, v8, v9
	v_lshlrev_b32_e32 v8, 16, v1
	v_and_b32_e32 v9, 0xffff0000, v1
	v_rcp_f32_e32 v1, v5
	s_nop 0
	v_mul_f32_e32 v5, v18, v1
	v_rcp_f32_e32 v1, v4
	s_nop 0
	v_mul_f32_e32 v4, v16, v1
	v_or_b32_e32 v16, 24, v144
	v_pk_mul_f32 v[4:5], v[4:5], v[8:9]
	v_mad_u64_u32 v[8:9], s[6:7], v16, s72, v[70:71]
	global_load_dwordx4 v[8:11], v[8:9], off
	v_lshlrev_b32_e32 v13, 16, v6
	v_and_b32_e32 v6, 0xffff0000, v6
	v_mul_f32_e32 v1, 0xbfb8aa3b, v13
	v_exp_f32_e32 v18, v1
	v_mul_f32_e32 v1, 0xbfb8aa3b, v6
	v_exp_f32_e32 v19, v1
	v_cvt_pk_bf16_f32 v1, v4, v5
	v_lshlrev_b32_e32 v4, 16, v2
	v_and_b32_e32 v5, 0xffff0000, v2
	v_pk_add_f32 v[18:19], v[18:19], 1.0 op_sel_hi:[1,0]
	v_or_b32_e32 v144, 28, v144
	s_nop 0
	v_rcp_f32_e32 v2, v19
	s_nop 0
	v_mul_f32_e32 v19, v6, v2
	v_and_b32_e32 v21, 0xffff0000, v7
	v_lshlrev_b32_e32 v17, 16, v7
	v_mul_f32_e32 v6, 0xbfb8aa3b, v17
	v_mul_f32_e32 v7, 0xbfb8aa3b, v21
	v_exp_f32_e32 v6, v6
	v_exp_f32_e32 v7, v7
	v_rcp_f32_e32 v2, v18
	s_nop 0
	v_mul_f32_e32 v18, v13, v2
	v_pk_mul_f32 v[4:5], v[18:19], v[4:5]
	v_pk_add_f32 v[6:7], v[6:7], 1.0 op_sel_hi:[1,0]
	v_cvt_pk_bf16_f32 v2, v4, v5
	v_lshlrev_b32_e32 v4, 16, v3
	v_and_b32_e32 v5, 0xffff0000, v3
	v_rcp_f32_e32 v3, v7
	s_nop 0
	v_mul_f32_e32 v7, v21, v3
	v_rcp_f32_e32 v3, v6
	s_nop 0
	v_mul_f32_e32 v6, v17, v3
	v_pk_mul_f32 v[4:5], v[6:7], v[4:5]
	ds_read_b128 v[18:21], v12 offset:6528
	v_cvt_pk_bf16_f32 v3, v4, v5
	v_lshlrev_b64 v[4:5], 12, v[14:15]
	v_lshl_add_u64 v[14:15], v[68:69], 0, v[4:5]
	v_mad_u64_u32 v[4:5], s[6:7], v144, s72, v[70:71]
	global_load_dwordx4 v[4:7], v[4:5], off
	s_waitcnt vmcnt(1)
	v_lshlrev_b32_e32 v24, 16, v8
	v_and_b32_e32 v8, 0xffff0000, v8
	v_mul_f32_e32 v13, 0xbfb8aa3b, v24
	v_exp_f32_e32 v22, v13
	v_mul_f32_e32 v13, 0xbfb8aa3b, v8
	v_exp_f32_e32 v23, v13
	global_store_dwordx4 v[14:15], v[0:3], off offset:3072 sc1
	ds_read_b128 v[0:3], v12 offset:7616
	s_waitcnt lgkmcnt(1)
	v_lshlrev_b32_e32 v12, 16, v18
	v_pk_add_f32 v[14:15], v[22:23], 1.0 op_sel_hi:[1,0]
	v_and_b32_e32 v13, 0xffff0000, v18
	v_mov_b32_e32 v17, v145
	v_div_scale_f32 v22, s[6:7], v14, v14, v24
	v_rcp_f32_e32 v26, v22
	v_rcp_f32_e32 v18, v15
	s_nop 0
	v_mul_f32_e32 v15, v8, v18
	v_and_b32_e32 v25, 0xffff0000, v9
	v_fma_f32 v8, -v22, v26, 1.0
	v_fmac_f32_e32 v26, v8, v26
	v_lshlrev_b32_e32 v23, 16, v9
	v_mul_f32_e32 v8, 0xbfb8aa3b, v23
	v_mul_f32_e32 v9, 0xbfb8aa3b, v25
	v_exp_f32_e32 v8, v8
	v_exp_f32_e32 v9, v9
	v_rcp_f32_e32 v18, v14
	s_nop 0
	v_mul_f32_e32 v14, v24, v18
	v_pk_mul_f32 v[12:13], v[14:15], v[12:13]
	v_pk_add_f32 v[14:15], v[8:9], 1.0 op_sel_hi:[1,0]
	v_cvt_pk_bf16_f32 v8, v12, v13
	v_lshlrev_b32_e32 v12, 16, v19
	v_and_b32_e32 v13, 0xffff0000, v19
	v_div_scale_f32 v19, s[6:7], v14, v14, v23
	v_rcp_f32_e32 v24, v19
	v_rcp_f32_e32 v9, v15
	s_nop 0
	v_mul_f32_e32 v15, v25, v9
	v_lshlrev_b32_e32 v25, 16, v10
	v_fma_f32 v9, -v19, v24, 1.0
	v_fmac_f32_e32 v24, v9, v24
	v_and_b32_e32 v10, 0xffff0000, v10
	v_mul_f32_e32 v18, 0xbfb8aa3b, v25
	v_mul_f32_e32 v19, 0xbfb8aa3b, v10
	v_exp_f32_e32 v18, v18
	v_exp_f32_e32 v19, v19
	v_rcp_f32_e32 v9, v14
	s_nop 0
	v_mul_f32_e32 v14, v23, v9
	v_pk_mul_f32 v[12:13], v[14:15], v[12:13]
	v_pk_add_f32 v[14:15], v[18:19], 1.0 op_sel_hi:[1,0]
	v_cvt_pk_bf16_f32 v9, v12, v13
	v_lshlrev_b32_e32 v12, 16, v20
	v_and_b32_e32 v13, 0xffff0000, v20
	v_rcp_f32_e32 v18, v15
	s_nop 0
	v_mul_f32_e32 v15, v10, v18
	v_and_b32_e32 v22, 0xffff0000, v11
	v_lshlrev_b32_e32 v20, 16, v11
	v_mul_f32_e32 v10, 0xbfb8aa3b, v20
	v_mul_f32_e32 v11, 0xbfb8aa3b, v22
	v_exp_f32_e32 v10, v10
	v_exp_f32_e32 v11, v11
	v_rcp_f32_e32 v18, v14
	s_nop 0
	v_mul_f32_e32 v14, v25, v18
	v_pk_mul_f32 v[12:13], v[14:15], v[12:13]
	v_pk_add_f32 v[14:15], v[10:11], 1.0 op_sel_hi:[1,0]
	v_cvt_pk_bf16_f32 v10, v12, v13
	v_lshlrev_b32_e32 v12, 16, v21
	v_and_b32_e32 v13, 0xffff0000, v21
	v_div_scale_f32 v19, s[6:7], v14, v14, v20
	v_rcp_f32_e32 v23, v19
	v_rcp_f32_e32 v11, v15
	s_nop 0
	v_mul_f32_e32 v15, v22, v11
	v_fma_f32 v11, -v19, v23, 1.0
	v_fmac_f32_e32 v23, v11, v23
	v_div_scale_f32 v11, vcc, v20, v14, v20
	v_mul_f32_e32 v18, v11, v23
	v_fma_f32 v21, -v19, v18, v11
	s_waitcnt vmcnt(1)
	v_lshlrev_b32_e32 v18, 16, v4
	v_rcp_f32_e32 v11, v14
	s_nop 0
	v_mul_f32_e32 v14, v20, v11
	v_and_b32_e32 v4, 0xffff0000, v4
	v_mul_f32_e32 v11, 0xbfb8aa3b, v18
	v_pk_mul_f32 v[12:13], v[14:15], v[12:13]
	v_exp_f32_e32 v14, v11
	v_mul_f32_e32 v11, 0xbfb8aa3b, v4
	v_exp_f32_e32 v15, v11
	v_cvt_pk_bf16_f32 v11, v12, v13
	v_lshlrev_b64 v[12:13], 12, v[16:17]
	v_lshl_add_u64 v[12:13], v[68:69], 0, v[12:13]
	v_pk_add_f32 v[14:15], v[14:15], 1.0 op_sel_hi:[1,0]
	global_store_dwordx4 v[12:13], v[8:11], off offset:3072 sc1
	v_div_scale_f32 v16, s[6:7], v15, v15, v4
	v_rcp_f32_e32 v17, v16
	s_waitcnt lgkmcnt(0)
	v_lshlrev_b32_e32 v8, 16, v0
	v_and_b32_e32 v9, 0xffff0000, v0
	v_fma_f32 v0, -v16, v17, 1.0
	v_fmac_f32_e32 v17, v0, v17
	v_rcp_f32_e32 v0, v15
	s_nop 0
	v_mul_f32_e32 v11, v4, v0
	v_lshlrev_b32_e32 v12, 16, v5
	v_and_b32_e32 v15, 0xffff0000, v5
	v_mul_f32_e32 v4, 0xbfb8aa3b, v12
	v_mul_f32_e32 v5, 0xbfb8aa3b, v15
	v_exp_f32_e32 v4, v4
	v_exp_f32_e32 v5, v5
	v_rcp_f32_e32 v0, v14
	s_nop 0
	v_mul_f32_e32 v10, v18, v0
	v_pk_mul_f32 v[8:9], v[10:11], v[8:9]
	v_pk_add_f32 v[4:5], v[4:5], 1.0 op_sel_hi:[1,0]
	v_cvt_pk_bf16_f32 v0, v8, v9
	v_lshlrev_b32_e32 v8, 16, v1
	v_and_b32_e32 v9, 0xffff0000, v1
	v_div_scale_f32 v10, s[6:7], v4, v4, v12
	v_rcp_f32_e32 v14, v10
	v_rcp_f32_e32 v1, v5
	s_nop 0
	v_mul_f32_e32 v5, v15, v1
	v_lshlrev_b32_e32 v15, 16, v6
	v_fma_f32 v1, -v10, v14, 1.0
	v_fmac_f32_e32 v14, v1, v14
	v_and_b32_e32 v6, 0xffff0000, v6
	v_mul_f32_e32 v10, 0xbfb8aa3b, v15
	v_mul_f32_e32 v11, 0xbfb8aa3b, v6
	v_exp_f32_e32 v10, v10
	v_exp_f32_e32 v11, v11
	v_rcp_f32_e32 v1, v4
	s_nop 0
	v_mul_f32_e32 v4, v12, v1
	v_pk_mul_f32 v[4:5], v[4:5], v[8:9]
	v_pk_add_f32 v[8:9], v[10:11], 1.0 op_sel_hi:[1,0]
	v_cvt_pk_bf16_f32 v1, v4, v5
	v_lshlrev_b32_e32 v4, 16, v2
	v_and_b32_e32 v5, 0xffff0000, v2
	v_rcp_f32_e32 v2, v9
	s_nop 0
	v_mul_f32_e32 v9, v6, v2
	v_and_b32_e32 v12, 0xffff0000, v7
	v_lshlrev_b32_e32 v10, 16, v7
	v_mul_f32_e32 v6, 0xbfb8aa3b, v10
	v_mul_f32_e32 v7, 0xbfb8aa3b, v12
	v_exp_f32_e32 v6, v6
	v_exp_f32_e32 v7, v7
	v_rcp_f32_e32 v2, v8
	s_nop 0
	v_mul_f32_e32 v8, v15, v2
	v_pk_mul_f32 v[4:5], v[8:9], v[4:5]
	v_pk_add_f32 v[6:7], v[6:7], 1.0 op_sel_hi:[1,0]
	v_cvt_pk_bf16_f32 v2, v4, v5
	v_lshlrev_b32_e32 v4, 16, v3
	v_and_b32_e32 v5, 0xffff0000, v3
	v_div_scale_f32 v8, s[6:7], v6, v6, v10
	v_rcp_f32_e32 v13, v8
	v_rcp_f32_e32 v3, v7
	s_nop 0
	v_mul_f32_e32 v7, v12, v3
	s_mov_b64 s[6:7], 0
	v_fma_f32 v3, -v8, v13, 1.0
	v_fmac_f32_e32 v13, v3, v13
	v_div_scale_f32 v3, vcc, v10, v6, v10
	v_mul_f32_e32 v9, v3, v13
	v_fma_f32 v11, -v8, v9, v3
	v_fmac_f32_e32 v9, v11, v13
	v_rcp_f32_e32 v3, v6
	s_nop 0
	v_mul_f32_e32 v6, v10, v3
	v_pk_mul_f32 v[4:5], v[6:7], v[4:5]
	s_nop 0
	v_cvt_pk_bf16_f32 v3, v4, v5
	v_lshlrev_b64 v[4:5], 12, v[144:145]
	v_lshl_add_u64 v[4:5], v[68:69], 0, v[4:5]
	global_store_dwordx4 v[4:5], v[0:3], off offset:3072 sc1
	s_barrier
